# GEMM K-loops: removed the already-satisfied duplicate s_waitcnt lgkmcnt(0) at the head of each MFMA block (segment-head trim)
# baseline (speedup 1.0000x reference)
; #define PG8_STAGE(bufoff, gbase, voff) do { _Pragma("unroll") for (int _i = 0; _i < 2; ++_i) \
;         __builtin_amdgcn_global_load_lds((const unsigned*)((const char*)(gbase) + (voff)[_i]), (LAS unsigned*)(lds + (bufoff) + ldsw + _i * 8192), 16, 0, 0); } while (0)
; #define PG8_LDA(dst, b, h) do { _Pragma("unroll") for (int m = 0; m < 4; ++m) _Pragma("unroll") for (int k = 0; k < 2; ++k) dst[m][k] = *(const LAS bf16x8*)(lds + PG8_SA(b, h) + aoff + m * 2048 + k * 1024); } while (0)
; #define PG8_LDB(dst, b, h) do { _Pragma("unroll") for (int n = 0; n < 2; ++n) _Pragma("unroll") for (int k = 0; k < 2; ++k) dst[n][k] = *(const LAS bf16x8*)(lds + PG8_SB(b, h) + boff + n * 2048 + k * 1024); } while (0)
; #define PG8_MMA(ai, bj, At, Bt) do { __builtin_amdgcn_s_setprio(1); _Pragma("unroll") for (int m = 0; m < 4; ++m) _Pragma("unroll") for (int n = 0; n < 2; ++n) _Pragma("unroll") for (int k = 0; k < 2; ++k) \
;         acc[ai][bj][m][n] = __builtin_amdgcn_mfma_f32_16x16x32_bf16(Bt[n][k], At[m][k], acc[ai][bj][m][n], 0, 0, 0); __builtin_amdgcn_s_setprio(0); } while (0)
; #define PG8_BAR __builtin_amdgcn_s_barrier()
; template <class Epi, bool ALIGN_EPI = true, bool SP2 = true>
; DI void gemm_phase(LAS unsigned char* lds, const Gemm g, const StaticOrder& S, const Epi& E) {
;     ...
;             const bool last = (t == nt - 2);
;             const char* a1 = cA + (size_t)(t + 1) * kstep;
;             const char* a2 = last ? nA : cA + (size_t)(t + 2) * kstep; const char* b2 = last ? nB : cB + (size_t)(t + 2) * kstep;
;             const char* a3 = a2 + kstep; const char* b3 = b2 + kstep;
;             if (Epi::MID) { if (t == (nt >> 1)) {
;                 if constexpr (ALIGN_EPI) { if (wr == 0) PG8_BAR; }
;                 E.mid(acc, cur, wr, wc, fr, fq);
;                 if constexpr (ALIGN_EPI) { if (wr == 1) PG8_BAR; } } }
;             if constexpr (SP2) {
;             PG8_LDB(B0, 0, 0); PG8_LDB(B1, 0, 1); PG8_SCHED; PG8_LDA(At, 0, 0); PG8_STAGE(PG8_SA(1, 1), a1 + hstepA, voffA);
;             PG8_WAIT_V(8); PG8_WAIT_L(0); PG8_BAR; PG8_MMA(0, 0, At, B0); PG8_MMA(0, 1, At, B1); PG8_BAR; PG8_SCHED;
;             PG8_LDA(At, 0, 1); PG8_STAGE(PG8_SB(0, 0), b2, voffB); PG8_STAGE(PG8_SB(0, 1), b2 + hstepB, voffB); PG8_STAGE(PG8_SA(0, 0), a2, voffA);
;             PG8_WAIT_V(8); PG8_WAIT_L(0); PG8_BAR; PG8_MMA(1, 0, At, B0); PG8_MMA(1, 1, At, B1); PG8_BAR; PG8_SCHED;
.LBB0_261:
	ds_read_b128 v[150:153], v147
	ds_read_b128 v[154:157], v147 offset:1024
	ds_read_b128 v[158:161], v147 offset:2048
	ds_read_b128 v[162:165], v147 offset:3072
	ds_read_b128 v[166:169], v148
	ds_read_b128 v[170:173], v148 offset:1024
	ds_read_b128 v[174:177], v148 offset:2048
	ds_read_b128 v[178:181], v148 offset:3072
	s_add_u32 s46, s34, 0xfff00080
	s_addc_u32 s47, s35, -1
	s_cmp_eq_u32 s78, 60
	s_cselect_b32 s49, s25, s47
	s_cselect_b32 s48, s74, s46
	s_cselect_b32 s47, s23, s77
	s_cselect_b32 s46, s75, s76
	v_lshl_add_u64 v[216:217], s[34:35], 0, v[136:137]
	s_add_i32 m0, s21, 0xc000
	ds_read_b128 v[182:185], v149
	ds_read_b128 v[186:189], v149 offset:1024
	ds_read_b128 v[192:195], v149 offset:2048
	ds_read_b128 v[196:199], v149 offset:3072
	ds_read_b128 v[200:203], v149 offset:4096
	ds_read_b128 v[204:207], v149 offset:5120
	ds_read_b128 v[208:211], v149 offset:6144
	ds_read_b128 v[212:215], v149 offset:7168
	global_load_lds_dwordx4 v[216:217], off
	v_lshl_add_u64 v[216:217], s[34:35], 0, v[138:139]
	s_add_i32 m0, s21, 0xe000
	s_nop 0
	global_load_lds_dwordx4 v[216:217], off
	s_waitcnt vmcnt(8)
	s_waitcnt lgkmcnt(0)
	s_barrier
	v_mfma_f32_16x16x32_bf16 v[124:127], v[150:153], v[182:185], v[124:127]
	v_mfma_f32_16x16x32_bf16 v[120:123], v[158:161], v[182:185], v[120:123]
	v_mfma_f32_16x16x32_bf16 v[116:119], v[150:153], v[192:195], v[116:119]
	v_mfma_f32_16x16x32_bf16 v[112:115], v[158:161], v[192:195], v[112:115]
	v_mfma_f32_16x16x32_bf16 v[100:103], v[150:153], v[200:203], v[100:103]
	v_mfma_f32_16x16x32_bf16 v[96:99], v[158:161], v[200:203], v[96:99]
	v_mfma_f32_16x16x32_bf16 v[84:87], v[150:153], v[208:211], v[84:87]
	v_mfma_f32_16x16x32_bf16 v[80:83], v[158:161], v[208:211], v[80:83]
	v_mfma_f32_16x16x32_bf16 v[124:127], v[154:157], v[186:189], v[124:127]
	v_mfma_f32_16x16x32_bf16 v[120:123], v[162:165], v[186:189], v[120:123]
	v_mfma_f32_16x16x32_bf16 v[116:119], v[154:157], v[196:199], v[116:119]
	v_mfma_f32_16x16x32_bf16 v[112:115], v[162:165], v[196:199], v[112:115]
	v_mfma_f32_16x16x32_bf16 v[100:103], v[154:157], v[204:207], v[100:103]
	v_mfma_f32_16x16x32_bf16 v[96:99], v[162:165], v[204:207], v[96:99]
	v_mfma_f32_16x16x32_bf16 v[84:87], v[154:157], v[212:215], v[84:87]
	v_mfma_f32_16x16x32_bf16 v[80:83], v[162:165], v[212:215], v[80:83]
	v_mfma_f32_16x16x32_bf16 v[108:111], v[166:169], v[182:185], v[108:111]
	v_mfma_f32_16x16x32_bf16 v[104:107], v[174:177], v[182:185], v[104:107]
	v_mfma_f32_16x16x32_bf16 v[92:95], v[166:169], v[192:195], v[92:95]
	v_mfma_f32_16x16x32_bf16 v[88:91], v[174:177], v[192:195], v[88:91]
	v_mfma_f32_16x16x32_bf16 v[76:79], v[166:169], v[200:203], v[76:79]
	v_mfma_f32_16x16x32_bf16 v[72:75], v[174:177], v[200:203], v[72:75]
	v_mfma_f32_16x16x32_bf16 v[68:71], v[166:169], v[208:211], v[68:71]
	v_mfma_f32_16x16x32_bf16 v[64:67], v[174:177], v[208:211], v[64:67]
	v_mfma_f32_16x16x32_bf16 v[108:111], v[170:173], v[186:189], v[108:111]
	v_mfma_f32_16x16x32_bf16 v[104:107], v[178:181], v[186:189], v[104:107]
	v_mfma_f32_16x16x32_bf16 v[92:95], v[170:173], v[196:199], v[92:95]
	v_mfma_f32_16x16x32_bf16 v[88:91], v[178:181], v[196:199], v[88:91]
	v_mfma_f32_16x16x32_bf16 v[76:79], v[170:173], v[204:207], v[76:79]
	v_mfma_f32_16x16x32_bf16 v[72:75], v[178:181], v[204:207], v[72:75]
	v_mfma_f32_16x16x32_bf16 v[68:71], v[170:173], v[212:215], v[68:71]
	v_mfma_f32_16x16x32_bf16 v[64:67], v[178:181], v[212:215], v[64:67]
	s_barrier
	s_add_i32 s79, s70, s51
	v_lshl_add_u64 v[216:217], s[46:47], 0, v[132:133]
	s_mov_b32 m0, s79
	ds_read_b128 v[182:185], v149 offset:16384
	ds_read_b128 v[186:189], v149 offset:17408
	ds_read_b128 v[192:195], v149 offset:18432
	ds_read_b128 v[196:199], v149 offset:19456
	ds_read_b128 v[200:203], v149 offset:20480
	ds_read_b128 v[204:207], v149 offset:21504
	ds_read_b128 v[208:211], v149 offset:22528
	ds_read_b128 v[212:215], v149 offset:23552
	global_load_lds_dwordx4 v[216:217], off
	s_add_i32 m0, s79, 0x2000
	s_add_u32 s80, s46, 0x100000
	v_lshl_add_u64 v[218:219], s[46:47], 0, v[128:129]
	s_addc_u32 s81, s47, 0
	s_add_i32 s79, s71, s51
	global_load_lds_dwordx4 v[218:219], off
	v_lshl_add_u64 v[220:221], s[80:81], 0, v[132:133]
	s_mov_b32 m0, s79
	v_lshl_add_u64 v[222:223], s[48:49], 0, v[130:131]
	global_load_lds_dwordx4 v[220:221], off
	v_lshl_add_u64 v[220:221], s[80:81], 0, v[128:129]
	s_add_i32 m0, s79, 0x2000
	s_nop 0
	global_load_lds_dwordx4 v[220:221], off
	v_lshl_add_u64 v[220:221], s[48:49], 0, v[134:135]
	s_mov_b32 m0, s21
	s_nop 0
	global_load_lds_dwordx4 v[220:221], off
	s_mov_b32 m0, s62
	s_nop 0
	global_load_lds_dwordx4 v[222:223], off
	s_waitcnt vmcnt(8)
	s_waitcnt lgkmcnt(0)
	s_barrier
; #define PG8_STAGE(bufoff, gbase, voff) do { _Pragma("unroll") for (int _i = 0; _i < 2; ++_i) \
;         __builtin_amdgcn_global_load_lds((const unsigned*)((const char*)(gbase) + (voff)[_i]), (LAS unsigned*)(lds + (bufoff) + ldsw + _i * 8192), 16, 0, 0); } while (0)
; #define PG8_LDA(dst, b, h) do { _Pragma("unroll") for (int m = 0; m < 4; ++m) _Pragma("unroll") for (int k = 0; k < 2; ++k) dst[m][k] = *(const LAS bf16x8*)(lds + PG8_SA(b, h) + aoff + m * 2048 + k * 1024); } while (0)
; #define PG8_LDB(dst, b, h) do { _Pragma("unroll") for (int n = 0; n < 2; ++n) _Pragma("unroll") for (int k = 0; k < 2; ++k) dst[n][k] = *(const LAS bf16x8*)(lds + PG8_SB(b, h) + boff + n * 2048 + k * 1024); } while (0)
; #define PG8_MMA(ai, bj, At, Bt) do { __builtin_amdgcn_s_setprio(1); _Pragma("unroll") for (int m = 0; m < 4; ++m) _Pragma("unroll") for (int n = 0; n < 2; ++n) _Pragma("unroll") for (int k = 0; k < 2; ++k) \
;         acc[ai][bj][m][n] = __builtin_amdgcn_mfma_f32_16x16x32_bf16(Bt[n][k], At[m][k], acc[ai][bj][m][n], 0, 0, 0); __builtin_amdgcn_s_setprio(0); } while (0)
; #define PG8_WAIT_V(n) asm volatile("s_waitcnt vmcnt(" #n ")" ::: "memory")
; #define PG8_WAIT_L(n) asm volatile("s_waitcnt lgkmcnt(" #n ")" ::: "memory")
; #define PG8_BAR __builtin_amdgcn_s_barrier()
; #define PG8_SCHED __builtin_amdgcn_sched_barrier(0)
; template <class Epi, bool ALIGN_EPI = true, bool SP2 = true>
; DI void gemm_phase(LAS unsigned char* lds, const Gemm g, const StaticOrder& S, const Epi& E) {
;     ...
;             PG8_WAIT_V(8); PG8_WAIT_L(0); PG8_BAR; PG8_MMA(1, 0, At, B0); PG8_MMA(1, 1, At, B1); PG8_BAR; PG8_SCHED;
;             PG8_LDB(B0, 1, 0); PG8_LDB(B1, 1, 1); PG8_SCHED; PG8_LDA(At, 1, 0); PG8_STAGE(PG8_SA(0, 1), a2 + hstepA, voffA);
;             PG8_WAIT_V(8); PG8_WAIT_L(0); PG8_BAR; PG8_MMA(0, 0, At, B0); PG8_MMA(0, 1, At, B1); PG8_BAR; PG8_SCHED;
	v_mfma_f32_16x16x32_bf16 v[60:63], v[150:153], v[182:185], v[60:63]
	v_mfma_f32_16x16x32_bf16 v[56:59], v[158:161], v[182:185], v[56:59]
	v_mfma_f32_16x16x32_bf16 v[52:55], v[150:153], v[192:195], v[52:55]
	v_mfma_f32_16x16x32_bf16 v[48:51], v[158:161], v[192:195], v[48:51]
	v_mfma_f32_16x16x32_bf16 v[36:39], v[150:153], v[200:203], v[36:39]
	v_mfma_f32_16x16x32_bf16 v[32:35], v[158:161], v[200:203], v[32:35]
	v_mfma_f32_16x16x32_bf16 v[20:23], v[150:153], v[208:211], v[20:23]
	v_mfma_f32_16x16x32_bf16 v[16:19], v[158:161], v[208:211], v[16:19]
	v_mfma_f32_16x16x32_bf16 v[60:63], v[154:157], v[186:189], v[60:63]
	v_mfma_f32_16x16x32_bf16 v[56:59], v[162:165], v[186:189], v[56:59]
	v_mfma_f32_16x16x32_bf16 v[52:55], v[154:157], v[196:199], v[52:55]
	v_mfma_f32_16x16x32_bf16 v[48:51], v[162:165], v[196:199], v[48:51]
	v_mfma_f32_16x16x32_bf16 v[36:39], v[154:157], v[204:207], v[36:39]
	v_mfma_f32_16x16x32_bf16 v[32:35], v[162:165], v[204:207], v[32:35]
	v_mfma_f32_16x16x32_bf16 v[20:23], v[154:157], v[212:215], v[20:23]
	v_mfma_f32_16x16x32_bf16 v[16:19], v[162:165], v[212:215], v[16:19]
	v_mfma_f32_16x16x32_bf16 v[44:47], v[166:169], v[182:185], v[44:47]
	v_mfma_f32_16x16x32_bf16 v[40:43], v[174:177], v[182:185], v[40:43]
	v_mfma_f32_16x16x32_bf16 v[28:31], v[166:169], v[192:195], v[28:31]
	v_mfma_f32_16x16x32_bf16 v[24:27], v[174:177], v[192:195], v[24:27]
	v_mfma_f32_16x16x32_bf16 v[12:15], v[166:169], v[200:203], v[12:15]
	v_mfma_f32_16x16x32_bf16 v[8:11], v[174:177], v[200:203], v[8:11]
	v_mfma_f32_16x16x32_bf16 v[4:7], v[166:169], v[208:211], v[4:7]
	v_mfma_f32_16x16x32_bf16 v[0:3], v[174:177], v[208:211], v[0:3]
	v_mfma_f32_16x16x32_bf16 v[44:47], v[170:173], v[186:189], v[44:47]
	v_mfma_f32_16x16x32_bf16 v[40:43], v[178:181], v[186:189], v[40:43]
	v_mfma_f32_16x16x32_bf16 v[28:31], v[170:173], v[196:199], v[28:31]
	v_mfma_f32_16x16x32_bf16 v[24:27], v[178:181], v[196:199], v[24:27]
	v_mfma_f32_16x16x32_bf16 v[12:15], v[170:173], v[204:207], v[12:15]
	v_mfma_f32_16x16x32_bf16 v[8:11], v[178:181], v[204:207], v[8:11]
	v_mfma_f32_16x16x32_bf16 v[4:7], v[170:173], v[212:215], v[4:7]
	v_mfma_f32_16x16x32_bf16 v[0:3], v[178:181], v[212:215], v[0:3]
	s_barrier
	s_add_i32 s79, 0, 0x18000
	s_add_i32 s80, 0, 0x1c000
	v_add_u32_e32 v162, s79, v145
	v_add_u32_e32 v178, s80, v145
	ds_read_b128 v[150:153], v162
	ds_read_b128 v[154:157], v162 offset:1024
	ds_read_b128 v[158:161], v162 offset:2048
	ds_read_b128 v[162:165], v162 offset:3072
	ds_read_b128 v[166:169], v178
	ds_read_b128 v[170:173], v178 offset:1024
	ds_read_b128 v[174:177], v178 offset:2048
	ds_read_b128 v[178:181], v178 offset:3072
	s_add_u32 s48, s48, 0x100000
	s_addc_u32 s49, s49, 0
	s_mov_b32 m0, s63
	v_lshl_add_u64 v[226:227], s[48:49], 0, v[134:135]
	ds_read_b128 v[182:185], v149 offset:32768
	ds_read_b128 v[186:189], v149 offset:33792
	ds_read_b128 v[192:195], v149 offset:34816
	ds_read_b128 v[196:199], v149 offset:35840
	ds_read_b128 v[200:203], v149 offset:36864
	ds_read_b128 v[204:207], v149 offset:37888
	ds_read_b128 v[208:211], v149 offset:38912
	ds_read_b128 v[212:215], v149 offset:39936
	global_load_lds_dwordx4 v[226:227], off
	v_lshl_add_u64 v[226:227], s[48:49], 0, v[130:131]
	s_mov_b32 m0, s64
	s_nop 0
	global_load_lds_dwordx4 v[226:227], off
	s_waitcnt vmcnt(8)
	s_waitcnt lgkmcnt(0)
	s_barrier
	v_mfma_f32_16x16x32_bf16 v[124:127], v[150:153], v[182:185], v[124:127]
	v_mfma_f32_16x16x32_bf16 v[120:123], v[158:161], v[182:185], v[120:123]
	v_mfma_f32_16x16x32_bf16 v[116:119], v[150:153], v[192:195], v[116:119]
	v_mfma_f32_16x16x32_bf16 v[112:115], v[158:161], v[192:195], v[112:115]
	v_mfma_f32_16x16x32_bf16 v[100:103], v[150:153], v[200:203], v[100:103]
	v_mfma_f32_16x16x32_bf16 v[96:99], v[158:161], v[200:203], v[96:99]
	v_mfma_f32_16x16x32_bf16 v[84:87], v[150:153], v[208:211], v[84:87]
	v_mfma_f32_16x16x32_bf16 v[80:83], v[158:161], v[208:211], v[80:83]
	v_mfma_f32_16x16x32_bf16 v[124:127], v[154:157], v[186:189], v[124:127]
	v_mfma_f32_16x16x32_bf16 v[120:123], v[162:165], v[186:189], v[120:123]
	v_mfma_f32_16x16x32_bf16 v[116:119], v[154:157], v[196:199], v[116:119]
	v_mfma_f32_16x16x32_bf16 v[112:115], v[162:165], v[196:199], v[112:115]
	v_mfma_f32_16x16x32_bf16 v[100:103], v[154:157], v[204:207], v[100:103]
	v_mfma_f32_16x16x32_bf16 v[96:99], v[162:165], v[204:207], v[96:99]
	v_mfma_f32_16x16x32_bf16 v[84:87], v[154:157], v[212:215], v[84:87]
	v_mfma_f32_16x16x32_bf16 v[80:83], v[162:165], v[212:215], v[80:83]
	v_mfma_f32_16x16x32_bf16 v[108:111], v[166:169], v[182:185], v[108:111]
	v_mfma_f32_16x16x32_bf16 v[104:107], v[174:177], v[182:185], v[104:107]
	v_mfma_f32_16x16x32_bf16 v[92:95], v[166:169], v[192:195], v[92:95]
	v_mfma_f32_16x16x32_bf16 v[88:91], v[174:177], v[192:195], v[88:91]
	v_mfma_f32_16x16x32_bf16 v[76:79], v[166:169], v[200:203], v[76:79]
	v_mfma_f32_16x16x32_bf16 v[72:75], v[174:177], v[200:203], v[72:75]
	v_mfma_f32_16x16x32_bf16 v[68:71], v[166:169], v[208:211], v[68:71]
	v_mfma_f32_16x16x32_bf16 v[64:67], v[174:177], v[208:211], v[64:67]
	v_mfma_f32_16x16x32_bf16 v[108:111], v[170:173], v[186:189], v[108:111]
	v_mfma_f32_16x16x32_bf16 v[104:107], v[178:181], v[186:189], v[104:107]
	v_mfma_f32_16x16x32_bf16 v[92:95], v[170:173], v[196:199], v[92:95]
	v_mfma_f32_16x16x32_bf16 v[88:91], v[178:181], v[196:199], v[88:91]
	v_mfma_f32_16x16x32_bf16 v[76:79], v[170:173], v[204:207], v[76:79]
	v_mfma_f32_16x16x32_bf16 v[72:75], v[178:181], v[204:207], v[72:75]
	v_mfma_f32_16x16x32_bf16 v[68:71], v[170:173], v[212:215], v[68:71]
	v_mfma_f32_16x16x32_bf16 v[64:67], v[178:181], v[212:215], v[64:67]
	s_barrier
; #define PG8_STAGE(bufoff, gbase, voff) do { _Pragma("unroll") for (int _i = 0; _i < 2; ++_i) \
;         __builtin_amdgcn_global_load_lds((const unsigned*)((const char*)(gbase) + (voff)[_i]), (LAS unsigned*)(lds + (bufoff) + ldsw + _i * 8192), 16, 0, 0); } while (0)
; #define PG8_LDA(dst, b, h) do { _Pragma("unroll") for (int m = 0; m < 4; ++m) _Pragma("unroll") for (int k = 0; k < 2; ++k) dst[m][k] = *(const LAS bf16x8*)(lds + PG8_SA(b, h) + aoff + m * 2048 + k * 1024); } while (0)
; #define PG8_MMA(ai, bj, At, Bt) do { __builtin_amdgcn_s_setprio(1); _Pragma("unroll") for (int m = 0; m < 4; ++m) _Pragma("unroll") for (int n = 0; n < 2; ++n) _Pragma("unroll") for (int k = 0; k < 2; ++k) \
;         acc[ai][bj][m][n] = __builtin_amdgcn_mfma_f32_16x16x32_bf16(Bt[n][k], At[m][k], acc[ai][bj][m][n], 0, 0, 0); __builtin_amdgcn_s_setprio(0); } while (0)
; #define PG8_WAIT_V(n) asm volatile("s_waitcnt vmcnt(" #n ")" ::: "memory")
; #define PG8_WAIT_L(n) asm volatile("s_waitcnt lgkmcnt(" #n ")" ::: "memory")
; #define PG8_BAR __builtin_amdgcn_s_barrier()
; #define PG8_SCHED __builtin_amdgcn_sched_barrier(0)
; template <class Epi, bool ALIGN_EPI = true, bool SP2 = true>
; DI void gemm_phase(LAS unsigned char* lds, const Gemm g, const StaticOrder& S, const Epi& E) {
;     ...
;             PG8_LDA(At, 1, 1); PG8_STAGE(PG8_SB(1, 0), b3, voffB); PG8_STAGE(PG8_SB(1, 1), b3 + hstepB, voffB); PG8_STAGE(PG8_SA(1, 0), a3, voffA);
;             PG8_WAIT_V(8); PG8_WAIT_L(0); PG8_BAR; PG8_MMA(1, 0, At, B0); PG8_MMA(1, 1, At, B1); PG8_BAR; PG8_SCHED;
;     ...
;         if constexpr (ALIGN_EPI) { if (wr == 0) PG8_BAR; }
	s_add_i32 s48, s79, s51
	v_lshl_add_u64 v[216:217], v[216:217], 0, s[10:11]
	s_mov_b32 m0, s48
	ds_read_b128 v[182:185], v149 offset:49152
	ds_read_b128 v[186:189], v149 offset:50176
	ds_read_b128 v[192:195], v149 offset:51200
	ds_read_b128 v[196:199], v149 offset:52224
	ds_read_b128 v[200:203], v149 offset:53248
	ds_read_b128 v[204:207], v149 offset:54272
	ds_read_b128 v[208:211], v149 offset:55296
	ds_read_b128 v[212:215], v149 offset:56320
	global_load_lds_dwordx4 v[216:217], off
	s_add_i32 m0, s48, 0x2000
	s_add_u32 s46, s46, 0x100080
	v_lshl_add_u64 v[216:217], v[218:219], 0, s[10:11]
	s_addc_u32 s47, s47, 0
	s_add_i32 s48, s80, s51
	global_load_lds_dwordx4 v[216:217], off
	v_lshl_add_u64 v[216:217], s[46:47], 0, v[132:133]
	s_mov_b32 m0, s48
	s_nop 0
	global_load_lds_dwordx4 v[216:217], off
	v_lshl_add_u64 v[216:217], s[46:47], 0, v[128:129]
	s_add_i32 m0, s48, 0x2000
	s_nop 0
	global_load_lds_dwordx4 v[216:217], off
	v_lshl_add_u64 v[216:217], v[220:221], 0, s[10:11]
	s_mov_b32 m0, s66
	s_nop 0
	global_load_lds_dwordx4 v[216:217], off
	v_lshl_add_u64 v[216:217], v[222:223], 0, s[10:11]
	s_mov_b32 m0, s67
	s_nop 0
	global_load_lds_dwordx4 v[216:217], off
	s_waitcnt vmcnt(8)
	s_waitcnt lgkmcnt(0)
	s_barrier
	v_mfma_f32_16x16x32_bf16 v[60:63], v[150:153], v[182:185], v[60:63]
	v_mfma_f32_16x16x32_bf16 v[56:59], v[158:161], v[182:185], v[56:59]
	v_mfma_f32_16x16x32_bf16 v[52:55], v[150:153], v[192:195], v[52:55]
	v_mfma_f32_16x16x32_bf16 v[48:51], v[158:161], v[192:195], v[48:51]
	v_mfma_f32_16x16x32_bf16 v[36:39], v[150:153], v[200:203], v[36:39]
	v_mfma_f32_16x16x32_bf16 v[32:35], v[158:161], v[200:203], v[32:35]
	v_mfma_f32_16x16x32_bf16 v[20:23], v[150:153], v[208:211], v[20:23]
	v_mfma_f32_16x16x32_bf16 v[16:19], v[158:161], v[208:211], v[16:19]
	v_mfma_f32_16x16x32_bf16 v[60:63], v[154:157], v[186:189], v[60:63]
	v_mfma_f32_16x16x32_bf16 v[56:59], v[162:165], v[186:189], v[56:59]
	v_mfma_f32_16x16x32_bf16 v[52:55], v[154:157], v[196:199], v[52:55]
	v_mfma_f32_16x16x32_bf16 v[48:51], v[162:165], v[196:199], v[48:51]
	v_mfma_f32_16x16x32_bf16 v[36:39], v[154:157], v[204:207], v[36:39]
	v_mfma_f32_16x16x32_bf16 v[32:35], v[162:165], v[204:207], v[32:35]
	v_mfma_f32_16x16x32_bf16 v[20:23], v[154:157], v[212:215], v[20:23]
	v_mfma_f32_16x16x32_bf16 v[16:19], v[162:165], v[212:215], v[16:19]
	v_mfma_f32_16x16x32_bf16 v[44:47], v[166:169], v[182:185], v[44:47]
	v_mfma_f32_16x16x32_bf16 v[40:43], v[174:177], v[182:185], v[40:43]
	v_mfma_f32_16x16x32_bf16 v[28:31], v[166:169], v[192:195], v[28:31]
	v_mfma_f32_16x16x32_bf16 v[24:27], v[174:177], v[192:195], v[24:27]
	v_mfma_f32_16x16x32_bf16 v[12:15], v[166:169], v[200:203], v[12:15]
	v_mfma_f32_16x16x32_bf16 v[8:11], v[174:177], v[200:203], v[8:11]
	v_mfma_f32_16x16x32_bf16 v[4:7], v[166:169], v[208:211], v[4:7]
	v_mfma_f32_16x16x32_bf16 v[0:3], v[174:177], v[208:211], v[0:3]
	v_mfma_f32_16x16x32_bf16 v[44:47], v[170:173], v[186:189], v[44:47]
	v_mfma_f32_16x16x32_bf16 v[40:43], v[178:181], v[186:189], v[40:43]
	v_mfma_f32_16x16x32_bf16 v[28:31], v[170:173], v[196:199], v[28:31]
	v_mfma_f32_16x16x32_bf16 v[24:27], v[178:181], v[196:199], v[24:27]
	v_mfma_f32_16x16x32_bf16 v[12:15], v[170:173], v[204:207], v[12:15]
	v_mfma_f32_16x16x32_bf16 v[8:11], v[178:181], v[204:207], v[8:11]
	v_mfma_f32_16x16x32_bf16 v[4:7], v[170:173], v[212:215], v[4:7]
	v_mfma_f32_16x16x32_bf16 v[0:3], v[178:181], v[212:215], v[0:3]
	s_barrier
	s_add_i32 s78, s78, 2
	s_add_u32 s34, s34, 0x100
	s_addc_u32 s35, s35, 0
	s_add_u32 s76, s76, 0x100
	s_addc_u32 s77, s77, 0
	s_cmp_gt_u32 s78, 61
	s_cbranch_scc0 .LBB0_261
	s_and_b64 vcc, exec, s[18:19]
	s_cbranch_vccz .LBB0_264
	s_barrier

; #define PG8_STAGE(bufoff, gbase, voff) do { _Pragma("unroll") for (int _i = 0; _i < 2; ++_i) \
;         __builtin_amdgcn_global_load_lds((const unsigned*)((const char*)(gbase) + (voff)[_i]), (LAS unsigned*)(lds + (bufoff) + ldsw + _i * 8192), 16, 0, 0); } while (0)
; #define PG8_LDA(dst, b, h) do { _Pragma("unroll") for (int m = 0; m < 4; ++m) _Pragma("unroll") for (int k = 0; k < 2; ++k) dst[m][k] = *(const LAS bf16x8*)(lds + PG8_SA(b, h) + aoff + m * 2048 + k * 1024); } while (0)
; #define PG8_LDB(dst, b, h) do { _Pragma("unroll") for (int n = 0; n < 2; ++n) _Pragma("unroll") for (int k = 0; k < 2; ++k) dst[n][k] = *(const LAS bf16x8*)(lds + PG8_SB(b, h) + boff + n * 2048 + k * 1024); } while (0)
; #define PG8_MMA(ai, bj, At, Bt) do { __builtin_amdgcn_s_setprio(1); _Pragma("unroll") for (int m = 0; m < 4; ++m) _Pragma("unroll") for (int n = 0; n < 2; ++n) _Pragma("unroll") for (int k = 0; k < 2; ++k) \
;         acc[ai][bj][m][n] = __builtin_amdgcn_mfma_f32_16x16x32_bf16(Bt[n][k], At[m][k], acc[ai][bj][m][n], 0, 0, 0); __builtin_amdgcn_s_setprio(0); } while (0)
; #define PG8_BAR __builtin_amdgcn_s_barrier()
; template <class Epi, bool ALIGN_EPI = true, bool SP2 = true>
; DI void gemm_phase(LAS unsigned char* lds, const Gemm g, const StaticOrder& S, const Epi& E) {
;     ...
;             const bool last = (t == nt - 2);
;             const char* a1 = cA + (size_t)(t + 1) * kstep;
;             const char* a2 = last ? nA : cA + (size_t)(t + 2) * kstep; const char* b2 = last ? nB : cB + (size_t)(t + 2) * kstep;
;             const char* a3 = a2 + kstep; const char* b3 = b2 + kstep;
;             if (Epi::MID) { if (t == (nt >> 1)) {
;                 if constexpr (ALIGN_EPI) { if (wr == 0) PG8_BAR; }
;                 E.mid(acc, cur, wr, wc, fr, fq);
;                 if constexpr (ALIGN_EPI) { if (wr == 1) PG8_BAR; } } }
;             if constexpr (SP2) {
;             PG8_LDB(B0, 0, 0); PG8_LDB(B1, 0, 1); PG8_SCHED; PG8_LDA(At, 0, 0); PG8_STAGE(PG8_SA(1, 1), a1 + hstepA, voffA);
;             PG8_WAIT_V(8); PG8_WAIT_L(0); PG8_BAR; PG8_MMA(0, 0, At, B0); PG8_MMA(0, 1, At, B1); PG8_BAR; PG8_SCHED;
;             PG8_LDA(At, 0, 1); PG8_STAGE(PG8_SB(0, 0), b2, voffB); PG8_STAGE(PG8_SB(0, 1), b2 + hstepB, voffB); PG8_STAGE(PG8_SA(0, 0), a2, voffA);
;             PG8_WAIT_V(8); PG8_WAIT_L(0); PG8_BAR; PG8_MMA(1, 0, At, B0); PG8_MMA(1, 1, At, B1); PG8_BAR; PG8_SCHED;
.LBB0_334:
	ds_read_b128 v[162:165], v158
	ds_read_b128 v[166:169], v158 offset:1024
	ds_read_b128 v[170:173], v158 offset:2048
	ds_read_b128 v[174:177], v158 offset:3072
	ds_read_b128 v[178:181], v159
	ds_read_b128 v[182:185], v159 offset:1024
	ds_read_b128 v[186:189], v159 offset:2048
	ds_read_b128 v[192:195], v159 offset:3072
	s_add_u32 s30, s0, 0xffb80080
	s_addc_u32 s31, s1, -1
	s_cmp_eq_u32 s76, 12
	s_cselect_b32 s35, s25, s31
	s_cselect_b32 s34, s24, s30
	s_cselect_b32 s31, s23, s75
	s_cselect_b32 s30, s73, s74
	v_lshl_add_u64 v[230:231], s[0:1], 0, v[136:137]
	s_add_i32 m0, s49, 0xc000
	ds_read_b128 v[196:199], v160
	ds_read_b128 v[200:203], v160 offset:1024
	ds_read_b128 v[204:207], v160 offset:2048
	ds_read_b128 v[208:211], v160 offset:3072
	ds_read_b128 v[212:215], v160 offset:4096
	ds_read_b128 v[216:219], v160 offset:5120
	ds_read_b128 v[220:223], v160 offset:6144
	ds_read_b128 v[226:229], v160 offset:7168
	global_load_lds_dwordx4 v[230:231], off
	v_lshl_add_u64 v[230:231], s[0:1], 0, v[138:139]
	s_add_i32 m0, s49, 0xe000
	s_nop 0
	global_load_lds_dwordx4 v[230:231], off
	s_waitcnt vmcnt(8)
	s_waitcnt lgkmcnt(0)
	s_barrier
	v_mfma_f32_16x16x32_bf16 v[124:127], v[162:165], v[196:199], v[124:127]
	v_mfma_f32_16x16x32_bf16 v[120:123], v[170:173], v[196:199], v[120:123]
	v_mfma_f32_16x16x32_bf16 v[116:119], v[162:165], v[204:207], v[116:119]
	v_mfma_f32_16x16x32_bf16 v[112:115], v[170:173], v[204:207], v[112:115]
	v_mfma_f32_16x16x32_bf16 v[100:103], v[162:165], v[212:215], v[100:103]
	v_mfma_f32_16x16x32_bf16 v[96:99], v[170:173], v[212:215], v[96:99]
	v_mfma_f32_16x16x32_bf16 v[84:87], v[162:165], v[220:223], v[84:87]
	v_mfma_f32_16x16x32_bf16 v[80:83], v[170:173], v[220:223], v[80:83]
	v_mfma_f32_16x16x32_bf16 v[124:127], v[166:169], v[200:203], v[124:127]
	v_mfma_f32_16x16x32_bf16 v[120:123], v[174:177], v[200:203], v[120:123]
	v_mfma_f32_16x16x32_bf16 v[116:119], v[166:169], v[208:211], v[116:119]
	v_mfma_f32_16x16x32_bf16 v[112:115], v[174:177], v[208:211], v[112:115]
	v_mfma_f32_16x16x32_bf16 v[100:103], v[166:169], v[216:219], v[100:103]
	v_mfma_f32_16x16x32_bf16 v[96:99], v[174:177], v[216:219], v[96:99]
	v_mfma_f32_16x16x32_bf16 v[84:87], v[166:169], v[226:229], v[84:87]
	v_mfma_f32_16x16x32_bf16 v[80:83], v[174:177], v[226:229], v[80:83]
	v_mfma_f32_16x16x32_bf16 v[108:111], v[178:181], v[196:199], v[108:111]
	v_mfma_f32_16x16x32_bf16 v[104:107], v[186:189], v[196:199], v[104:107]
	v_mfma_f32_16x16x32_bf16 v[92:95], v[178:181], v[204:207], v[92:95]
	v_mfma_f32_16x16x32_bf16 v[88:91], v[186:189], v[204:207], v[88:91]
	v_mfma_f32_16x16x32_bf16 v[76:79], v[178:181], v[212:215], v[76:79]
	v_mfma_f32_16x16x32_bf16 v[72:75], v[186:189], v[212:215], v[72:75]
	v_mfma_f32_16x16x32_bf16 v[68:71], v[178:181], v[220:223], v[68:71]
	v_mfma_f32_16x16x32_bf16 v[64:67], v[186:189], v[220:223], v[64:67]
	v_mfma_f32_16x16x32_bf16 v[108:111], v[182:185], v[200:203], v[108:111]
	v_mfma_f32_16x16x32_bf16 v[104:107], v[192:195], v[200:203], v[104:107]
	v_mfma_f32_16x16x32_bf16 v[92:95], v[182:185], v[208:211], v[92:95]
	v_mfma_f32_16x16x32_bf16 v[88:91], v[192:195], v[208:211], v[88:91]
	v_mfma_f32_16x16x32_bf16 v[76:79], v[182:185], v[216:219], v[76:79]
	v_mfma_f32_16x16x32_bf16 v[72:75], v[192:195], v[216:219], v[72:75]
	v_mfma_f32_16x16x32_bf16 v[68:71], v[182:185], v[226:229], v[68:71]
	v_mfma_f32_16x16x32_bf16 v[64:67], v[192:195], v[226:229], v[64:67]
	s_barrier
	s_add_i32 s77, s67, s47
	v_lshl_add_u64 v[230:231], s[30:31], 0, v[134:135]
	s_mov_b32 m0, s77
	ds_read_b128 v[196:199], v160 offset:16384
	ds_read_b128 v[200:203], v160 offset:17408
	ds_read_b128 v[204:207], v160 offset:18432
	ds_read_b128 v[208:211], v160 offset:19456
	ds_read_b128 v[212:215], v160 offset:20480
	ds_read_b128 v[216:219], v160 offset:21504
	ds_read_b128 v[220:223], v160 offset:22528
	ds_read_b128 v[226:229], v160 offset:23552
	global_load_lds_dwordx4 v[230:231], off
	s_add_i32 m0, s77, 0x2000
	s_add_u32 s78, s30, 0x40000
	v_lshl_add_u64 v[232:233], s[30:31], 0, v[132:133]
	s_addc_u32 s79, s31, 0
	s_add_i32 s77, s68, s47
	global_load_lds_dwordx4 v[232:233], off
	v_lshl_add_u64 v[234:235], s[78:79], 0, v[134:135]
	s_mov_b32 m0, s77
	v_lshl_add_u64 v[236:237], s[34:35], 0, v[130:131]
	global_load_lds_dwordx4 v[234:235], off
	v_lshl_add_u64 v[234:235], s[78:79], 0, v[132:133]
	s_add_i32 m0, s77, 0x2000
	s_nop 0
	global_load_lds_dwordx4 v[234:235], off
	v_lshl_add_u64 v[234:235], s[34:35], 0, v[128:129]
	s_mov_b32 m0, s49
	s_nop 0
	global_load_lds_dwordx4 v[234:235], off
	s_mov_b32 m0, s50
	s_nop 0
	global_load_lds_dwordx4 v[236:237], off
	s_waitcnt vmcnt(8)
	s_waitcnt lgkmcnt(0)
	s_barrier
; #define PG8_STAGE(bufoff, gbase, voff) do { _Pragma("unroll") for (int _i = 0; _i < 2; ++_i) \
;         __builtin_amdgcn_global_load_lds((const unsigned*)((const char*)(gbase) + (voff)[_i]), (LAS unsigned*)(lds + (bufoff) + ldsw + _i * 8192), 16, 0, 0); } while (0)
; #define PG8_LDA(dst, b, h) do { _Pragma("unroll") for (int m = 0; m < 4; ++m) _Pragma("unroll") for (int k = 0; k < 2; ++k) dst[m][k] = *(const LAS bf16x8*)(lds + PG8_SA(b, h) + aoff + m * 2048 + k * 1024); } while (0)
; #define PG8_LDB(dst, b, h) do { _Pragma("unroll") for (int n = 0; n < 2; ++n) _Pragma("unroll") for (int k = 0; k < 2; ++k) dst[n][k] = *(const LAS bf16x8*)(lds + PG8_SB(b, h) + boff + n * 2048 + k * 1024); } while (0)
; #define PG8_MMA(ai, bj, At, Bt) do { __builtin_amdgcn_s_setprio(1); _Pragma("unroll") for (int m = 0; m < 4; ++m) _Pragma("unroll") for (int n = 0; n < 2; ++n) _Pragma("unroll") for (int k = 0; k < 2; ++k) \
;         acc[ai][bj][m][n] = __builtin_amdgcn_mfma_f32_16x16x32_bf16(Bt[n][k], At[m][k], acc[ai][bj][m][n], 0, 0, 0); __builtin_amdgcn_s_setprio(0); } while (0)
; #define PG8_WAIT_V(n) asm volatile("s_waitcnt vmcnt(" #n ")" ::: "memory")
; #define PG8_WAIT_L(n) asm volatile("s_waitcnt lgkmcnt(" #n ")" ::: "memory")
; #define PG8_BAR __builtin_amdgcn_s_barrier()
; #define PG8_SCHED __builtin_amdgcn_sched_barrier(0)
; template <class Epi, bool ALIGN_EPI = true, bool SP2 = true>
; DI void gemm_phase(LAS unsigned char* lds, const Gemm g, const StaticOrder& S, const Epi& E) {
;     ...
;             PG8_WAIT_V(8); PG8_WAIT_L(0); PG8_BAR; PG8_MMA(1, 0, At, B0); PG8_MMA(1, 1, At, B1); PG8_BAR; PG8_SCHED;
;             PG8_LDB(B0, 1, 0); PG8_LDB(B1, 1, 1); PG8_SCHED; PG8_LDA(At, 1, 0); PG8_STAGE(PG8_SA(0, 1), a2 + hstepA, voffA);
;             PG8_WAIT_V(8); PG8_WAIT_L(0); PG8_BAR; PG8_MMA(0, 0, At, B0); PG8_MMA(0, 1, At, B1); PG8_BAR; PG8_SCHED;
	v_mfma_f32_16x16x32_bf16 v[60:63], v[162:165], v[196:199], v[60:63]
	v_mfma_f32_16x16x32_bf16 v[56:59], v[170:173], v[196:199], v[56:59]
	v_mfma_f32_16x16x32_bf16 v[52:55], v[162:165], v[204:207], v[52:55]
	v_mfma_f32_16x16x32_bf16 v[48:51], v[170:173], v[204:207], v[48:51]
	v_mfma_f32_16x16x32_bf16 v[36:39], v[162:165], v[212:215], v[36:39]
	v_mfma_f32_16x16x32_bf16 v[32:35], v[170:173], v[212:215], v[32:35]
	v_mfma_f32_16x16x32_bf16 v[20:23], v[162:165], v[220:223], v[20:23]
	v_mfma_f32_16x16x32_bf16 v[16:19], v[170:173], v[220:223], v[16:19]
	v_mfma_f32_16x16x32_bf16 v[60:63], v[166:169], v[200:203], v[60:63]
	v_mfma_f32_16x16x32_bf16 v[56:59], v[174:177], v[200:203], v[56:59]
	v_mfma_f32_16x16x32_bf16 v[52:55], v[166:169], v[208:211], v[52:55]
	v_mfma_f32_16x16x32_bf16 v[48:51], v[174:177], v[208:211], v[48:51]
	v_mfma_f32_16x16x32_bf16 v[36:39], v[166:169], v[216:219], v[36:39]
	v_mfma_f32_16x16x32_bf16 v[32:35], v[174:177], v[216:219], v[32:35]
	v_mfma_f32_16x16x32_bf16 v[20:23], v[166:169], v[226:229], v[20:23]
	v_mfma_f32_16x16x32_bf16 v[16:19], v[174:177], v[226:229], v[16:19]
	v_mfma_f32_16x16x32_bf16 v[44:47], v[178:181], v[196:199], v[44:47]
	v_mfma_f32_16x16x32_bf16 v[40:43], v[186:189], v[196:199], v[40:43]
	v_mfma_f32_16x16x32_bf16 v[28:31], v[178:181], v[204:207], v[28:31]
	v_mfma_f32_16x16x32_bf16 v[24:27], v[186:189], v[204:207], v[24:27]
	v_mfma_f32_16x16x32_bf16 v[12:15], v[178:181], v[212:215], v[12:15]
	v_mfma_f32_16x16x32_bf16 v[8:11], v[186:189], v[212:215], v[8:11]
	v_mfma_f32_16x16x32_bf16 v[4:7], v[178:181], v[220:223], v[4:7]
	v_mfma_f32_16x16x32_bf16 v[0:3], v[186:189], v[220:223], v[0:3]
	v_mfma_f32_16x16x32_bf16 v[44:47], v[182:185], v[200:203], v[44:47]
	v_mfma_f32_16x16x32_bf16 v[40:43], v[192:195], v[200:203], v[40:43]
	v_mfma_f32_16x16x32_bf16 v[28:31], v[182:185], v[208:211], v[28:31]
	v_mfma_f32_16x16x32_bf16 v[24:27], v[192:195], v[208:211], v[24:27]
	v_mfma_f32_16x16x32_bf16 v[12:15], v[182:185], v[216:219], v[12:15]
	v_mfma_f32_16x16x32_bf16 v[8:11], v[192:195], v[216:219], v[8:11]
	v_mfma_f32_16x16x32_bf16 v[4:7], v[182:185], v[226:229], v[4:7]
	v_mfma_f32_16x16x32_bf16 v[0:3], v[192:195], v[226:229], v[0:3]
	s_barrier
	s_add_i32 s77, 0, 0x18000
	v_add_u32_e32 v161, s77, v156
	s_add_i32 s78, 0, 0x1c000
	ds_read_b128 v[162:165], v161
	ds_read_b128 v[166:169], v161 offset:1024
	ds_read_b128 v[170:173], v161 offset:2048
	ds_read_b128 v[174:177], v161 offset:3072
	v_add_u32_e32 v161, s78, v156
	ds_read_b128 v[178:181], v161
	ds_read_b128 v[182:185], v161 offset:1024
	ds_read_b128 v[186:189], v161 offset:2048
	ds_read_b128 v[192:195], v161 offset:3072
	s_add_u32 s34, s34, 0x480000
	s_addc_u32 s35, s35, 0
	s_mov_b32 m0, s51
	v_lshl_add_u64 v[238:239], s[34:35], 0, v[128:129]
	ds_read_b128 v[196:199], v160 offset:32768
	ds_read_b128 v[200:203], v160 offset:33792
	ds_read_b128 v[204:207], v160 offset:34816
	ds_read_b128 v[208:211], v160 offset:35840
	ds_read_b128 v[212:215], v160 offset:36864
	ds_read_b128 v[216:219], v160 offset:37888
	ds_read_b128 v[220:223], v160 offset:38912
	ds_read_b128 v[226:229], v160 offset:39936
	global_load_lds_dwordx4 v[238:239], off
	v_lshl_add_u64 v[238:239], s[34:35], 0, v[130:131]
	s_mov_b32 m0, s60
	s_nop 0
	global_load_lds_dwordx4 v[238:239], off
	s_waitcnt vmcnt(8)
	s_waitcnt lgkmcnt(0)
	s_barrier
	v_mfma_f32_16x16x32_bf16 v[124:127], v[162:165], v[196:199], v[124:127]
	v_mfma_f32_16x16x32_bf16 v[120:123], v[170:173], v[196:199], v[120:123]
	v_mfma_f32_16x16x32_bf16 v[116:119], v[162:165], v[204:207], v[116:119]
	v_mfma_f32_16x16x32_bf16 v[112:115], v[170:173], v[204:207], v[112:115]
	v_mfma_f32_16x16x32_bf16 v[100:103], v[162:165], v[212:215], v[100:103]
	v_mfma_f32_16x16x32_bf16 v[96:99], v[170:173], v[212:215], v[96:99]
	v_mfma_f32_16x16x32_bf16 v[84:87], v[162:165], v[220:223], v[84:87]
	v_mfma_f32_16x16x32_bf16 v[80:83], v[170:173], v[220:223], v[80:83]
	v_mfma_f32_16x16x32_bf16 v[124:127], v[166:169], v[200:203], v[124:127]
	v_mfma_f32_16x16x32_bf16 v[120:123], v[174:177], v[200:203], v[120:123]
	v_mfma_f32_16x16x32_bf16 v[116:119], v[166:169], v[208:211], v[116:119]
	v_mfma_f32_16x16x32_bf16 v[112:115], v[174:177], v[208:211], v[112:115]
	v_mfma_f32_16x16x32_bf16 v[100:103], v[166:169], v[216:219], v[100:103]
	v_mfma_f32_16x16x32_bf16 v[96:99], v[174:177], v[216:219], v[96:99]
	v_mfma_f32_16x16x32_bf16 v[84:87], v[166:169], v[226:229], v[84:87]
	v_mfma_f32_16x16x32_bf16 v[80:83], v[174:177], v[226:229], v[80:83]
	v_mfma_f32_16x16x32_bf16 v[108:111], v[178:181], v[196:199], v[108:111]
	v_mfma_f32_16x16x32_bf16 v[104:107], v[186:189], v[196:199], v[104:107]
	v_mfma_f32_16x16x32_bf16 v[92:95], v[178:181], v[204:207], v[92:95]
	v_mfma_f32_16x16x32_bf16 v[88:91], v[186:189], v[204:207], v[88:91]
	v_mfma_f32_16x16x32_bf16 v[76:79], v[178:181], v[212:215], v[76:79]
	v_mfma_f32_16x16x32_bf16 v[72:75], v[186:189], v[212:215], v[72:75]
	v_mfma_f32_16x16x32_bf16 v[68:71], v[178:181], v[220:223], v[68:71]
	v_mfma_f32_16x16x32_bf16 v[64:67], v[186:189], v[220:223], v[64:67]
	v_mfma_f32_16x16x32_bf16 v[108:111], v[182:185], v[200:203], v[108:111]
	v_mfma_f32_16x16x32_bf16 v[104:107], v[192:195], v[200:203], v[104:107]
	v_mfma_f32_16x16x32_bf16 v[92:95], v[182:185], v[208:211], v[92:95]
	v_mfma_f32_16x16x32_bf16 v[88:91], v[192:195], v[208:211], v[88:91]
	v_mfma_f32_16x16x32_bf16 v[76:79], v[182:185], v[216:219], v[76:79]
	v_mfma_f32_16x16x32_bf16 v[72:75], v[192:195], v[216:219], v[72:75]
	v_mfma_f32_16x16x32_bf16 v[68:71], v[182:185], v[226:229], v[68:71]
	v_mfma_f32_16x16x32_bf16 v[64:67], v[192:195], v[226:229], v[64:67]
	s_barrier
; #define PG8_STAGE(bufoff, gbase, voff) do { _Pragma("unroll") for (int _i = 0; _i < 2; ++_i) \
;         __builtin_amdgcn_global_load_lds((const unsigned*)((const char*)(gbase) + (voff)[_i]), (LAS unsigned*)(lds + (bufoff) + ldsw + _i * 8192), 16, 0, 0); } while (0)
; #define PG8_LDA(dst, b, h) do { _Pragma("unroll") for (int m = 0; m < 4; ++m) _Pragma("unroll") for (int k = 0; k < 2; ++k) dst[m][k] = *(const LAS bf16x8*)(lds + PG8_SA(b, h) + aoff + m * 2048 + k * 1024); } while (0)
; #define PG8_MMA(ai, bj, At, Bt) do { __builtin_amdgcn_s_setprio(1); _Pragma("unroll") for (int m = 0; m < 4; ++m) _Pragma("unroll") for (int n = 0; n < 2; ++n) _Pragma("unroll") for (int k = 0; k < 2; ++k) \
;         acc[ai][bj][m][n] = __builtin_amdgcn_mfma_f32_16x16x32_bf16(Bt[n][k], At[m][k], acc[ai][bj][m][n], 0, 0, 0); __builtin_amdgcn_s_setprio(0); } while (0)
; #define PG8_WAIT_V(n) asm volatile("s_waitcnt vmcnt(" #n ")" ::: "memory")
; #define PG8_WAIT_L(n) asm volatile("s_waitcnt lgkmcnt(" #n ")" ::: "memory")
; #define PG8_BAR __builtin_amdgcn_s_barrier()
; #define PG8_SCHED __builtin_amdgcn_sched_barrier(0)
; template <class Epi, bool ALIGN_EPI = true, bool SP2 = true>
; DI void gemm_phase(LAS unsigned char* lds, const Gemm g, const StaticOrder& S, const Epi& E) {
;     ...
;             PG8_LDA(At, 1, 1); PG8_STAGE(PG8_SB(1, 0), b3, voffB); PG8_STAGE(PG8_SB(1, 1), b3 + hstepB, voffB); PG8_STAGE(PG8_SA(1, 0), a3, voffA);
;             PG8_WAIT_V(8); PG8_WAIT_L(0); PG8_BAR; PG8_MMA(1, 0, At, B0); PG8_MMA(1, 1, At, B1); PG8_BAR; PG8_SCHED;
;     ...
;         if constexpr (ALIGN_EPI) { if (wr == 0) PG8_BAR; }
	s_add_i32 s34, s77, s47
	v_lshl_add_u64 v[230:231], v[230:231], 0, s[18:19]
	s_mov_b32 m0, s34
	ds_read_b128 v[196:199], v160 offset:49152
	ds_read_b128 v[200:203], v160 offset:50176
	ds_read_b128 v[204:207], v160 offset:51200
	ds_read_b128 v[208:211], v160 offset:52224
	ds_read_b128 v[212:215], v160 offset:53248
	ds_read_b128 v[216:219], v160 offset:54272
	ds_read_b128 v[220:223], v160 offset:55296
	ds_read_b128 v[226:229], v160 offset:56320
	global_load_lds_dwordx4 v[230:231], off
	s_add_i32 m0, s34, 0x2000
	s_add_u32 s30, s30, 0x40080
	v_lshl_add_u64 v[230:231], v[232:233], 0, s[18:19]
	s_addc_u32 s31, s31, 0
	s_add_i32 s34, s78, s47
	global_load_lds_dwordx4 v[230:231], off
	v_lshl_add_u64 v[230:231], s[30:31], 0, v[134:135]
	s_mov_b32 m0, s34
	s_nop 0
	global_load_lds_dwordx4 v[230:231], off
	v_lshl_add_u64 v[230:231], s[30:31], 0, v[132:133]
	s_add_i32 m0, s34, 0x2000
	s_nop 0
	global_load_lds_dwordx4 v[230:231], off
	v_lshl_add_u64 v[230:231], v[234:235], 0, s[18:19]
	s_mov_b32 m0, s62
	s_nop 0
	global_load_lds_dwordx4 v[230:231], off
	v_lshl_add_u64 v[230:231], v[236:237], 0, s[18:19]
	s_mov_b32 m0, s63
	s_nop 0
	global_load_lds_dwordx4 v[230:231], off
	s_waitcnt vmcnt(8)
	s_waitcnt lgkmcnt(0)
	s_barrier
	v_mfma_f32_16x16x32_bf16 v[60:63], v[162:165], v[196:199], v[60:63]
	v_mfma_f32_16x16x32_bf16 v[56:59], v[170:173], v[196:199], v[56:59]
	v_mfma_f32_16x16x32_bf16 v[52:55], v[162:165], v[204:207], v[52:55]
	v_mfma_f32_16x16x32_bf16 v[48:51], v[170:173], v[204:207], v[48:51]
	v_mfma_f32_16x16x32_bf16 v[36:39], v[162:165], v[212:215], v[36:39]
	v_mfma_f32_16x16x32_bf16 v[32:35], v[170:173], v[212:215], v[32:35]
	v_mfma_f32_16x16x32_bf16 v[20:23], v[162:165], v[220:223], v[20:23]
	v_mfma_f32_16x16x32_bf16 v[16:19], v[170:173], v[220:223], v[16:19]
	v_mfma_f32_16x16x32_bf16 v[60:63], v[166:169], v[200:203], v[60:63]
	v_mfma_f32_16x16x32_bf16 v[56:59], v[174:177], v[200:203], v[56:59]
	v_mfma_f32_16x16x32_bf16 v[52:55], v[166:169], v[208:211], v[52:55]
	v_mfma_f32_16x16x32_bf16 v[48:51], v[174:177], v[208:211], v[48:51]
	v_mfma_f32_16x16x32_bf16 v[36:39], v[166:169], v[216:219], v[36:39]
	v_mfma_f32_16x16x32_bf16 v[32:35], v[174:177], v[216:219], v[32:35]
	v_mfma_f32_16x16x32_bf16 v[20:23], v[166:169], v[226:229], v[20:23]
	v_mfma_f32_16x16x32_bf16 v[16:19], v[174:177], v[226:229], v[16:19]
	v_mfma_f32_16x16x32_bf16 v[44:47], v[178:181], v[196:199], v[44:47]
	v_mfma_f32_16x16x32_bf16 v[40:43], v[186:189], v[196:199], v[40:43]
	v_mfma_f32_16x16x32_bf16 v[28:31], v[178:181], v[204:207], v[28:31]
	v_mfma_f32_16x16x32_bf16 v[24:27], v[186:189], v[204:207], v[24:27]
	v_mfma_f32_16x16x32_bf16 v[12:15], v[178:181], v[212:215], v[12:15]
	v_mfma_f32_16x16x32_bf16 v[8:11], v[186:189], v[212:215], v[8:11]
	v_mfma_f32_16x16x32_bf16 v[4:7], v[178:181], v[220:223], v[4:7]
	v_mfma_f32_16x16x32_bf16 v[0:3], v[186:189], v[220:223], v[0:3]
	v_mfma_f32_16x16x32_bf16 v[44:47], v[182:185], v[200:203], v[44:47]
	v_mfma_f32_16x16x32_bf16 v[40:43], v[192:195], v[200:203], v[40:43]
	v_mfma_f32_16x16x32_bf16 v[28:31], v[182:185], v[208:211], v[28:31]
	v_mfma_f32_16x16x32_bf16 v[24:27], v[192:195], v[208:211], v[24:27]
	v_mfma_f32_16x16x32_bf16 v[12:15], v[182:185], v[216:219], v[12:15]
	v_mfma_f32_16x16x32_bf16 v[8:11], v[192:195], v[216:219], v[8:11]
	v_mfma_f32_16x16x32_bf16 v[4:7], v[182:185], v[226:229], v[4:7]
	v_mfma_f32_16x16x32_bf16 v[0:3], v[192:195], v[226:229], v[0:3]
	s_barrier
	s_add_i32 s76, s76, 2
	s_add_u32 s0, s0, 0x100
	s_addc_u32 s1, s1, 0
	s_add_u32 s74, s74, 0x100
	s_addc_u32 s75, s75, 0
	s_cmp_gt_u32 s76, 13
	s_cbranch_scc0 .LBB0_334
	s_and_b64 vcc, exec, s[20:21]
	s_cbranch_vccz .LBB0_337
	s_barrier

; #define PG8_STAGE(bufoff, gbase, voff) do { _Pragma("unroll") for (int _i = 0; _i < 2; ++_i) \
;         __builtin_amdgcn_global_load_lds((const unsigned*)((const char*)(gbase) + (voff)[_i]), (LAS unsigned*)(lds + (bufoff) + ldsw + _i * 8192), 16, 0, 0); } while (0)
; #define PG8_LDA(dst, b, h) do { _Pragma("unroll") for (int m = 0; m < 4; ++m) _Pragma("unroll") for (int k = 0; k < 2; ++k) dst[m][k] = *(const LAS bf16x8*)(lds + PG8_SA(b, h) + aoff + m * 2048 + k * 1024); } while (0)
; #define PG8_LDB(dst, b, h) do { _Pragma("unroll") for (int n = 0; n < 2; ++n) _Pragma("unroll") for (int k = 0; k < 2; ++k) dst[n][k] = *(const LAS bf16x8*)(lds + PG8_SB(b, h) + boff + n * 2048 + k * 1024); } while (0)
; #define PG8_MMA(ai, bj, At, Bt) do { __builtin_amdgcn_s_setprio(1); _Pragma("unroll") for (int m = 0; m < 4; ++m) _Pragma("unroll") for (int n = 0; n < 2; ++n) _Pragma("unroll") for (int k = 0; k < 2; ++k) \
;         acc[ai][bj][m][n] = __builtin_amdgcn_mfma_f32_16x16x32_bf16(Bt[n][k], At[m][k], acc[ai][bj][m][n], 0, 0, 0); __builtin_amdgcn_s_setprio(0); } while (0)
; #define PG8_BAR __builtin_amdgcn_s_barrier()
; template <class Epi, bool ALIGN_EPI = true, bool SP2 = true>
; DI void gemm_phase(LAS unsigned char* lds, const Gemm g, const StaticOrder& S, const Epi& E) {
;     ...
;             const bool last = (t == nt - 2);
;             const char* a1 = cA + (size_t)(t + 1) * kstep;
;             const char* a2 = last ? nA : cA + (size_t)(t + 2) * kstep; const char* b2 = last ? nB : cB + (size_t)(t + 2) * kstep;
;             const char* a3 = a2 + kstep; const char* b3 = b2 + kstep;
;             if (Epi::MID) { if (t == (nt >> 1)) {
;                 if constexpr (ALIGN_EPI) { if (wr == 0) PG8_BAR; }
;                 E.mid(acc, cur, wr, wc, fr, fq);
;                 if constexpr (ALIGN_EPI) { if (wr == 1) PG8_BAR; } } }
;             if constexpr (SP2) {
;             PG8_LDB(B0, 0, 0); PG8_LDB(B1, 0, 1); PG8_SCHED; PG8_LDA(At, 0, 0); PG8_STAGE(PG8_SA(1, 1), a1 + hstepA, voffA);
;             PG8_WAIT_V(8); PG8_WAIT_L(0); PG8_BAR; PG8_MMA(0, 0, At, B0); PG8_MMA(0, 1, At, B1); PG8_BAR; PG8_SCHED;
;             PG8_LDA(At, 0, 1); PG8_STAGE(PG8_SB(0, 0), b2, voffB); PG8_STAGE(PG8_SB(0, 1), b2 + hstepB, voffB); PG8_STAGE(PG8_SA(0, 0), a2, voffA);
;             PG8_WAIT_V(8); PG8_WAIT_L(0); PG8_BAR; PG8_MMA(1, 0, At, B0); PG8_MMA(1, 1, At, B1); PG8_BAR; PG8_SCHED;
.LBB0_360:
	ds_read_b128 v[154:157], v144
	ds_read_b128 v[158:161], v144 offset:1024
	ds_read_b128 v[162:165], v144 offset:2048
	ds_read_b128 v[166:169], v144 offset:3072
	ds_read_b128 v[170:173], v145
	ds_read_b128 v[174:177], v145 offset:1024
	ds_read_b128 v[178:181], v145 offset:2048
	ds_read_b128 v[182:185], v145 offset:3072
	s_add_u32 s60, s0, 0xffb80080
	s_addc_u32 s61, s1, -1
	s_cmp_eq_u32 s90, 4
	s_cselect_b32 s63, s49, s61
	s_cselect_b32 s62, s48, s60
	s_cselect_b32 s61, s47, s89
	s_cselect_b32 s60, s87, s88
	v_lshl_add_u64 v[150:151], s[0:1], 0, v[136:137]
	s_add_i32 m0, s69, 0xc000
	ds_read_b128 v[186:189], v148
	ds_read_b128 v[192:195], v148 offset:1024
	ds_read_b128 v[196:199], v148 offset:2048
	ds_read_b128 v[200:203], v148 offset:3072
	ds_read_b128 v[204:207], v148 offset:4096
	ds_read_b128 v[208:211], v148 offset:5120
	ds_read_b128 v[212:215], v148 offset:6144
	ds_read_b128 v[216:219], v148 offset:7168
	global_load_lds_dwordx4 v[150:151], off
	v_lshl_add_u64 v[150:151], s[0:1], 0, v[138:139]
	s_add_i32 m0, s69, 0xe000
	s_nop 0
	global_load_lds_dwordx4 v[150:151], off
	s_waitcnt vmcnt(8)
	s_waitcnt lgkmcnt(0)
	s_barrier
	v_mfma_f32_16x16x32_bf16 v[124:127], v[154:157], v[186:189], v[124:127]
	v_mfma_f32_16x16x32_bf16 v[120:123], v[162:165], v[186:189], v[120:123]
	v_mfma_f32_16x16x32_bf16 v[116:119], v[154:157], v[196:199], v[116:119]
	v_mfma_f32_16x16x32_bf16 v[112:115], v[162:165], v[196:199], v[112:115]
	v_mfma_f32_16x16x32_bf16 v[100:103], v[154:157], v[204:207], v[100:103]
	v_mfma_f32_16x16x32_bf16 v[96:99], v[162:165], v[204:207], v[96:99]
	v_mfma_f32_16x16x32_bf16 v[84:87], v[154:157], v[212:215], v[84:87]
	v_mfma_f32_16x16x32_bf16 v[80:83], v[162:165], v[212:215], v[80:83]
	v_mfma_f32_16x16x32_bf16 v[124:127], v[158:161], v[192:195], v[124:127]
	v_mfma_f32_16x16x32_bf16 v[120:123], v[166:169], v[192:195], v[120:123]
	v_mfma_f32_16x16x32_bf16 v[116:119], v[158:161], v[200:203], v[116:119]
	v_mfma_f32_16x16x32_bf16 v[112:115], v[166:169], v[200:203], v[112:115]
	v_mfma_f32_16x16x32_bf16 v[100:103], v[158:161], v[208:211], v[100:103]
	v_mfma_f32_16x16x32_bf16 v[96:99], v[166:169], v[208:211], v[96:99]
	v_mfma_f32_16x16x32_bf16 v[84:87], v[158:161], v[216:219], v[84:87]
	v_mfma_f32_16x16x32_bf16 v[80:83], v[166:169], v[216:219], v[80:83]
	v_mfma_f32_16x16x32_bf16 v[108:111], v[170:173], v[186:189], v[108:111]
	v_mfma_f32_16x16x32_bf16 v[104:107], v[178:181], v[186:189], v[104:107]
	v_mfma_f32_16x16x32_bf16 v[92:95], v[170:173], v[196:199], v[92:95]
	v_mfma_f32_16x16x32_bf16 v[88:91], v[178:181], v[196:199], v[88:91]
	v_mfma_f32_16x16x32_bf16 v[76:79], v[170:173], v[204:207], v[76:79]
	v_mfma_f32_16x16x32_bf16 v[72:75], v[178:181], v[204:207], v[72:75]
	v_mfma_f32_16x16x32_bf16 v[68:71], v[170:173], v[212:215], v[68:71]
	v_mfma_f32_16x16x32_bf16 v[64:67], v[178:181], v[212:215], v[64:67]
	v_mfma_f32_16x16x32_bf16 v[108:111], v[174:177], v[192:195], v[108:111]
	v_mfma_f32_16x16x32_bf16 v[104:107], v[182:185], v[192:195], v[104:107]
	v_mfma_f32_16x16x32_bf16 v[92:95], v[174:177], v[200:203], v[92:95]
	v_mfma_f32_16x16x32_bf16 v[88:91], v[182:185], v[200:203], v[88:91]
	v_mfma_f32_16x16x32_bf16 v[76:79], v[174:177], v[208:211], v[76:79]
	v_mfma_f32_16x16x32_bf16 v[72:75], v[182:185], v[208:211], v[72:75]
	v_mfma_f32_16x16x32_bf16 v[68:71], v[174:177], v[216:219], v[68:71]
	v_mfma_f32_16x16x32_bf16 v[64:67], v[182:185], v[216:219], v[64:67]
	s_barrier
	s_add_i32 s91, s78, s68
	v_lshl_add_u64 v[150:151], s[60:61], 0, v[132:133]
	s_mov_b32 m0, s91
	ds_read_b128 v[186:189], v148 offset:16384
	ds_read_b128 v[192:195], v148 offset:17408
	ds_read_b128 v[196:199], v148 offset:18432
	ds_read_b128 v[200:203], v148 offset:19456
	ds_read_b128 v[204:207], v148 offset:20480
	ds_read_b128 v[208:211], v148 offset:21504
	ds_read_b128 v[212:215], v148 offset:22528
	ds_read_b128 v[216:219], v148 offset:23552
	global_load_lds_dwordx4 v[150:151], off
	s_add_i32 m0, s91, 0x2000
	s_add_u32 s92, s60, 0x20000
	v_lshl_add_u64 v[220:221], s[60:61], 0, v[134:135]
	s_addc_u32 s93, s61, 0
	s_add_i32 s91, s79, s68
	global_load_lds_dwordx4 v[220:221], off
	v_lshl_add_u64 v[222:223], s[92:93], 0, v[132:133]
	s_mov_b32 m0, s91
	v_lshl_add_u64 v[226:227], s[62:63], 0, v[130:131]
	global_load_lds_dwordx4 v[222:223], off
	v_lshl_add_u64 v[222:223], s[92:93], 0, v[134:135]
	s_add_i32 m0, s91, 0x2000
	s_nop 0
	global_load_lds_dwordx4 v[222:223], off
	v_lshl_add_u64 v[222:223], s[62:63], 0, v[128:129]
	s_mov_b32 m0, s69
	s_nop 0
	global_load_lds_dwordx4 v[222:223], off
	s_mov_b32 m0, s70
	s_nop 0
	global_load_lds_dwordx4 v[226:227], off
	s_waitcnt vmcnt(8)
	s_waitcnt lgkmcnt(0)
	s_barrier
; #define PG8_STAGE(bufoff, gbase, voff) do { _Pragma("unroll") for (int _i = 0; _i < 2; ++_i) \
;         __builtin_amdgcn_global_load_lds((const unsigned*)((const char*)(gbase) + (voff)[_i]), (LAS unsigned*)(lds + (bufoff) + ldsw + _i * 8192), 16, 0, 0); } while (0)
; #define PG8_LDA(dst, b, h) do { _Pragma("unroll") for (int m = 0; m < 4; ++m) _Pragma("unroll") for (int k = 0; k < 2; ++k) dst[m][k] = *(const LAS bf16x8*)(lds + PG8_SA(b, h) + aoff + m * 2048 + k * 1024); } while (0)
; #define PG8_LDB(dst, b, h) do { _Pragma("unroll") for (int n = 0; n < 2; ++n) _Pragma("unroll") for (int k = 0; k < 2; ++k) dst[n][k] = *(const LAS bf16x8*)(lds + PG8_SB(b, h) + boff + n * 2048 + k * 1024); } while (0)
; #define PG8_MMA(ai, bj, At, Bt) do { __builtin_amdgcn_s_setprio(1); _Pragma("unroll") for (int m = 0; m < 4; ++m) _Pragma("unroll") for (int n = 0; n < 2; ++n) _Pragma("unroll") for (int k = 0; k < 2; ++k) \
;         acc[ai][bj][m][n] = __builtin_amdgcn_mfma_f32_16x16x32_bf16(Bt[n][k], At[m][k], acc[ai][bj][m][n], 0, 0, 0); __builtin_amdgcn_s_setprio(0); } while (0)
; #define PG8_WAIT_V(n) asm volatile("s_waitcnt vmcnt(" #n ")" ::: "memory")
; #define PG8_WAIT_L(n) asm volatile("s_waitcnt lgkmcnt(" #n ")" ::: "memory")
; #define PG8_BAR __builtin_amdgcn_s_barrier()
; #define PG8_SCHED __builtin_amdgcn_sched_barrier(0)
; template <class Epi, bool ALIGN_EPI = true, bool SP2 = true>
; DI void gemm_phase(LAS unsigned char* lds, const Gemm g, const StaticOrder& S, const Epi& E) {
;     ...
;             PG8_WAIT_V(8); PG8_WAIT_L(0); PG8_BAR; PG8_MMA(1, 0, At, B0); PG8_MMA(1, 1, At, B1); PG8_BAR; PG8_SCHED;
;             PG8_LDB(B0, 1, 0); PG8_LDB(B1, 1, 1); PG8_SCHED; PG8_LDA(At, 1, 0); PG8_STAGE(PG8_SA(0, 1), a2 + hstepA, voffA);
;             PG8_WAIT_V(8); PG8_WAIT_L(0); PG8_BAR; PG8_MMA(0, 0, At, B0); PG8_MMA(0, 1, At, B1); PG8_BAR; PG8_SCHED;
	v_mfma_f32_16x16x32_bf16 v[60:63], v[154:157], v[186:189], v[60:63]
	v_mfma_f32_16x16x32_bf16 v[56:59], v[162:165], v[186:189], v[56:59]
	v_mfma_f32_16x16x32_bf16 v[52:55], v[154:157], v[196:199], v[52:55]
	v_mfma_f32_16x16x32_bf16 v[48:51], v[162:165], v[196:199], v[48:51]
	v_mfma_f32_16x16x32_bf16 v[36:39], v[154:157], v[204:207], v[36:39]
	v_mfma_f32_16x16x32_bf16 v[32:35], v[162:165], v[204:207], v[32:35]
	v_mfma_f32_16x16x32_bf16 v[20:23], v[154:157], v[212:215], v[20:23]
	v_mfma_f32_16x16x32_bf16 v[16:19], v[162:165], v[212:215], v[16:19]
	v_mfma_f32_16x16x32_bf16 v[60:63], v[158:161], v[192:195], v[60:63]
	v_mfma_f32_16x16x32_bf16 v[56:59], v[166:169], v[192:195], v[56:59]
	v_mfma_f32_16x16x32_bf16 v[52:55], v[158:161], v[200:203], v[52:55]
	v_mfma_f32_16x16x32_bf16 v[48:51], v[166:169], v[200:203], v[48:51]
	v_mfma_f32_16x16x32_bf16 v[36:39], v[158:161], v[208:211], v[36:39]
	v_mfma_f32_16x16x32_bf16 v[32:35], v[166:169], v[208:211], v[32:35]
	v_mfma_f32_16x16x32_bf16 v[20:23], v[158:161], v[216:219], v[20:23]
	v_mfma_f32_16x16x32_bf16 v[16:19], v[166:169], v[216:219], v[16:19]
	v_mfma_f32_16x16x32_bf16 v[44:47], v[170:173], v[186:189], v[44:47]
	v_mfma_f32_16x16x32_bf16 v[40:43], v[178:181], v[186:189], v[40:43]
	v_mfma_f32_16x16x32_bf16 v[28:31], v[170:173], v[196:199], v[28:31]
	v_mfma_f32_16x16x32_bf16 v[24:27], v[178:181], v[196:199], v[24:27]
	v_mfma_f32_16x16x32_bf16 v[12:15], v[170:173], v[204:207], v[12:15]
	v_mfma_f32_16x16x32_bf16 v[8:11], v[178:181], v[204:207], v[8:11]
	v_mfma_f32_16x16x32_bf16 v[4:7], v[170:173], v[212:215], v[4:7]
	v_mfma_f32_16x16x32_bf16 v[0:3], v[178:181], v[212:215], v[0:3]
	v_mfma_f32_16x16x32_bf16 v[44:47], v[174:177], v[192:195], v[44:47]
	v_mfma_f32_16x16x32_bf16 v[40:43], v[182:185], v[192:195], v[40:43]
	v_mfma_f32_16x16x32_bf16 v[28:31], v[174:177], v[200:203], v[28:31]
	v_mfma_f32_16x16x32_bf16 v[24:27], v[182:185], v[200:203], v[24:27]
	v_mfma_f32_16x16x32_bf16 v[12:15], v[174:177], v[208:211], v[12:15]
	v_mfma_f32_16x16x32_bf16 v[8:11], v[182:185], v[208:211], v[8:11]
	v_mfma_f32_16x16x32_bf16 v[4:7], v[174:177], v[216:219], v[4:7]
	v_mfma_f32_16x16x32_bf16 v[0:3], v[182:185], v[216:219], v[0:3]
	s_barrier
	s_add_i32 s91, 0, 0x18000
	v_add_u32_e32 v149, s91, v147
	s_add_i32 s92, 0, 0x1c000
	ds_read_b128 v[154:157], v149
	ds_read_b128 v[158:161], v149 offset:1024
	ds_read_b128 v[162:165], v149 offset:2048
	ds_read_b128 v[166:169], v149 offset:3072
	v_add_u32_e32 v149, s92, v147
	ds_read_b128 v[170:173], v149
	ds_read_b128 v[174:177], v149 offset:1024
	ds_read_b128 v[178:181], v149 offset:2048
	ds_read_b128 v[182:185], v149 offset:3072
	s_add_u32 s62, s62, 0x480000
	s_addc_u32 s63, s63, 0
	s_mov_b32 m0, s71
	v_lshl_add_u64 v[228:229], s[62:63], 0, v[128:129]
	ds_read_b128 v[186:189], v148 offset:32768
	ds_read_b128 v[192:195], v148 offset:33792
	ds_read_b128 v[196:199], v148 offset:34816
	ds_read_b128 v[200:203], v148 offset:35840
	ds_read_b128 v[204:207], v148 offset:36864
	ds_read_b128 v[208:211], v148 offset:37888
	ds_read_b128 v[212:215], v148 offset:38912
	ds_read_b128 v[216:219], v148 offset:39936
	global_load_lds_dwordx4 v[228:229], off
	v_lshl_add_u64 v[228:229], s[62:63], 0, v[130:131]
	s_mov_b32 m0, s72
	s_nop 0
	global_load_lds_dwordx4 v[228:229], off
	s_waitcnt vmcnt(8)
	s_waitcnt lgkmcnt(0)
	s_barrier
	v_mfma_f32_16x16x32_bf16 v[124:127], v[154:157], v[186:189], v[124:127]
	v_mfma_f32_16x16x32_bf16 v[120:123], v[162:165], v[186:189], v[120:123]
	v_mfma_f32_16x16x32_bf16 v[116:119], v[154:157], v[196:199], v[116:119]
	v_mfma_f32_16x16x32_bf16 v[112:115], v[162:165], v[196:199], v[112:115]
	v_mfma_f32_16x16x32_bf16 v[100:103], v[154:157], v[204:207], v[100:103]
	v_mfma_f32_16x16x32_bf16 v[96:99], v[162:165], v[204:207], v[96:99]
	v_mfma_f32_16x16x32_bf16 v[84:87], v[154:157], v[212:215], v[84:87]
	v_mfma_f32_16x16x32_bf16 v[80:83], v[162:165], v[212:215], v[80:83]
	v_mfma_f32_16x16x32_bf16 v[124:127], v[158:161], v[192:195], v[124:127]
	v_mfma_f32_16x16x32_bf16 v[120:123], v[166:169], v[192:195], v[120:123]
	v_mfma_f32_16x16x32_bf16 v[116:119], v[158:161], v[200:203], v[116:119]
	v_mfma_f32_16x16x32_bf16 v[112:115], v[166:169], v[200:203], v[112:115]
	v_mfma_f32_16x16x32_bf16 v[100:103], v[158:161], v[208:211], v[100:103]
	v_mfma_f32_16x16x32_bf16 v[96:99], v[166:169], v[208:211], v[96:99]
	v_mfma_f32_16x16x32_bf16 v[84:87], v[158:161], v[216:219], v[84:87]
	v_mfma_f32_16x16x32_bf16 v[80:83], v[166:169], v[216:219], v[80:83]
	v_mfma_f32_16x16x32_bf16 v[108:111], v[170:173], v[186:189], v[108:111]
	v_mfma_f32_16x16x32_bf16 v[104:107], v[178:181], v[186:189], v[104:107]
	v_mfma_f32_16x16x32_bf16 v[92:95], v[170:173], v[196:199], v[92:95]
	v_mfma_f32_16x16x32_bf16 v[88:91], v[178:181], v[196:199], v[88:91]
	v_mfma_f32_16x16x32_bf16 v[76:79], v[170:173], v[204:207], v[76:79]
	v_mfma_f32_16x16x32_bf16 v[72:75], v[178:181], v[204:207], v[72:75]
	v_mfma_f32_16x16x32_bf16 v[68:71], v[170:173], v[212:215], v[68:71]
	v_mfma_f32_16x16x32_bf16 v[64:67], v[178:181], v[212:215], v[64:67]
	v_mfma_f32_16x16x32_bf16 v[108:111], v[174:177], v[192:195], v[108:111]
	v_mfma_f32_16x16x32_bf16 v[104:107], v[182:185], v[192:195], v[104:107]
	v_mfma_f32_16x16x32_bf16 v[92:95], v[174:177], v[200:203], v[92:95]
	v_mfma_f32_16x16x32_bf16 v[88:91], v[182:185], v[200:203], v[88:91]
	v_mfma_f32_16x16x32_bf16 v[76:79], v[174:177], v[208:211], v[76:79]
	v_mfma_f32_16x16x32_bf16 v[72:75], v[182:185], v[208:211], v[72:75]
	v_mfma_f32_16x16x32_bf16 v[68:71], v[174:177], v[216:219], v[68:71]
	v_mfma_f32_16x16x32_bf16 v[64:67], v[182:185], v[216:219], v[64:67]
	s_barrier
; #define PG8_STAGE(bufoff, gbase, voff) do { _Pragma("unroll") for (int _i = 0; _i < 2; ++_i) \
;         __builtin_amdgcn_global_load_lds((const unsigned*)((const char*)(gbase) + (voff)[_i]), (LAS unsigned*)(lds + (bufoff) + ldsw + _i * 8192), 16, 0, 0); } while (0)
; #define PG8_LDA(dst, b, h) do { _Pragma("unroll") for (int m = 0; m < 4; ++m) _Pragma("unroll") for (int k = 0; k < 2; ++k) dst[m][k] = *(const LAS bf16x8*)(lds + PG8_SA(b, h) + aoff + m * 2048 + k * 1024); } while (0)
; #define PG8_MMA(ai, bj, At, Bt) do { __builtin_amdgcn_s_setprio(1); _Pragma("unroll") for (int m = 0; m < 4; ++m) _Pragma("unroll") for (int n = 0; n < 2; ++n) _Pragma("unroll") for (int k = 0; k < 2; ++k) \
;         acc[ai][bj][m][n] = __builtin_amdgcn_mfma_f32_16x16x32_bf16(Bt[n][k], At[m][k], acc[ai][bj][m][n], 0, 0, 0); __builtin_amdgcn_s_setprio(0); } while (0)
; #define PG8_WAIT_V(n) asm volatile("s_waitcnt vmcnt(" #n ")" ::: "memory")
; #define PG8_WAIT_L(n) asm volatile("s_waitcnt lgkmcnt(" #n ")" ::: "memory")
; #define PG8_BAR __builtin_amdgcn_s_barrier()
; #define PG8_SCHED __builtin_amdgcn_sched_barrier(0)
; template <class Epi, bool ALIGN_EPI = true, bool SP2 = true>
; DI void gemm_phase(LAS unsigned char* lds, const Gemm g, const StaticOrder& S, const Epi& E) {
;     ...
;             PG8_LDA(At, 1, 1); PG8_STAGE(PG8_SB(1, 0), b3, voffB); PG8_STAGE(PG8_SB(1, 1), b3 + hstepB, voffB); PG8_STAGE(PG8_SA(1, 0), a3, voffA);
;             PG8_WAIT_V(8); PG8_WAIT_L(0); PG8_BAR; PG8_MMA(1, 0, At, B0); PG8_MMA(1, 1, At, B1); PG8_BAR; PG8_SCHED;
;     ...
;         if constexpr (ALIGN_EPI) { if (wr == 0) PG8_BAR; }
	s_add_i32 s62, s91, s68
	v_lshl_add_u64 v[150:151], v[150:151], 0, s[20:21]
	s_mov_b32 m0, s62
	ds_read_b128 v[186:189], v148 offset:49152
	ds_read_b128 v[192:195], v148 offset:50176
	ds_read_b128 v[196:199], v148 offset:51200
	ds_read_b128 v[200:203], v148 offset:52224
	ds_read_b128 v[204:207], v148 offset:53248
	ds_read_b128 v[208:211], v148 offset:54272
	ds_read_b128 v[212:215], v148 offset:55296
	ds_read_b128 v[216:219], v148 offset:56320
	global_load_lds_dwordx4 v[150:151], off
	s_add_i32 m0, s62, 0x2000
	s_add_u32 s60, s60, 0x20080
	v_lshl_add_u64 v[150:151], v[220:221], 0, s[20:21]
	s_addc_u32 s61, s61, 0
	s_add_i32 s62, s92, s68
	global_load_lds_dwordx4 v[150:151], off
	v_lshl_add_u64 v[150:151], s[60:61], 0, v[132:133]
	s_mov_b32 m0, s62
	s_nop 0
	global_load_lds_dwordx4 v[150:151], off
	v_lshl_add_u64 v[150:151], s[60:61], 0, v[134:135]
	s_add_i32 m0, s62, 0x2000
	s_nop 0
	global_load_lds_dwordx4 v[150:151], off
	v_lshl_add_u64 v[150:151], v[222:223], 0, s[20:21]
	s_mov_b32 m0, s74
	s_nop 0
	global_load_lds_dwordx4 v[150:151], off
	v_lshl_add_u64 v[150:151], v[226:227], 0, s[20:21]
	s_mov_b32 m0, s75
	s_nop 0
	global_load_lds_dwordx4 v[150:151], off
	s_waitcnt vmcnt(8)
	s_waitcnt lgkmcnt(0)
	s_barrier
	v_mfma_f32_16x16x32_bf16 v[60:63], v[154:157], v[186:189], v[60:63]
	v_mfma_f32_16x16x32_bf16 v[56:59], v[162:165], v[186:189], v[56:59]
	v_mfma_f32_16x16x32_bf16 v[52:55], v[154:157], v[196:199], v[52:55]
	v_mfma_f32_16x16x32_bf16 v[48:51], v[162:165], v[196:199], v[48:51]
	v_mfma_f32_16x16x32_bf16 v[36:39], v[154:157], v[204:207], v[36:39]
	v_mfma_f32_16x16x32_bf16 v[32:35], v[162:165], v[204:207], v[32:35]
	v_mfma_f32_16x16x32_bf16 v[20:23], v[154:157], v[212:215], v[20:23]
	v_mfma_f32_16x16x32_bf16 v[16:19], v[162:165], v[212:215], v[16:19]
	v_mfma_f32_16x16x32_bf16 v[60:63], v[158:161], v[192:195], v[60:63]
	v_mfma_f32_16x16x32_bf16 v[56:59], v[166:169], v[192:195], v[56:59]
	v_mfma_f32_16x16x32_bf16 v[52:55], v[158:161], v[200:203], v[52:55]
	v_mfma_f32_16x16x32_bf16 v[48:51], v[166:169], v[200:203], v[48:51]
	v_mfma_f32_16x16x32_bf16 v[36:39], v[158:161], v[208:211], v[36:39]
	v_mfma_f32_16x16x32_bf16 v[32:35], v[166:169], v[208:211], v[32:35]
	v_mfma_f32_16x16x32_bf16 v[20:23], v[158:161], v[216:219], v[20:23]
	v_mfma_f32_16x16x32_bf16 v[16:19], v[166:169], v[216:219], v[16:19]
	v_mfma_f32_16x16x32_bf16 v[44:47], v[170:173], v[186:189], v[44:47]
	v_mfma_f32_16x16x32_bf16 v[40:43], v[178:181], v[186:189], v[40:43]
	v_mfma_f32_16x16x32_bf16 v[28:31], v[170:173], v[196:199], v[28:31]
	v_mfma_f32_16x16x32_bf16 v[24:27], v[178:181], v[196:199], v[24:27]
	v_mfma_f32_16x16x32_bf16 v[12:15], v[170:173], v[204:207], v[12:15]
	v_mfma_f32_16x16x32_bf16 v[8:11], v[178:181], v[204:207], v[8:11]
	v_mfma_f32_16x16x32_bf16 v[4:7], v[170:173], v[212:215], v[4:7]
	v_mfma_f32_16x16x32_bf16 v[0:3], v[178:181], v[212:215], v[0:3]
	v_mfma_f32_16x16x32_bf16 v[44:47], v[174:177], v[192:195], v[44:47]
	v_mfma_f32_16x16x32_bf16 v[40:43], v[182:185], v[192:195], v[40:43]
	v_mfma_f32_16x16x32_bf16 v[28:31], v[174:177], v[200:203], v[28:31]
	v_mfma_f32_16x16x32_bf16 v[24:27], v[182:185], v[200:203], v[24:27]
	v_mfma_f32_16x16x32_bf16 v[12:15], v[174:177], v[208:211], v[12:15]
	v_mfma_f32_16x16x32_bf16 v[8:11], v[182:185], v[208:211], v[8:11]
	v_mfma_f32_16x16x32_bf16 v[4:7], v[174:177], v[216:219], v[4:7]
	v_mfma_f32_16x16x32_bf16 v[0:3], v[182:185], v[216:219], v[0:3]
	s_barrier
	s_add_i32 s90, s90, 2
	s_add_u32 s0, s0, 0x100
	s_addc_u32 s1, s1, 0
	s_add_u32 s88, s88, 0x100
	s_addc_u32 s89, s89, 0
	s_cmp_gt_u32 s90, 5
	s_cbranch_scc0 .LBB0_360
	s_and_b64 vcc, exec, s[22:23]
	s_cbranch_vccz .LBB0_363
	s_barrier

; #define PG8_STAGE(bufoff, gbase, voff) do { _Pragma("unroll") for (int _i = 0; _i < 2; ++_i) \
;         __builtin_amdgcn_global_load_lds((const unsigned*)((const char*)(gbase) + (voff)[_i]), (LAS unsigned*)(lds + (bufoff) + ldsw + _i * 8192), 16, 0, 0); } while (0)
; #define PG8_LDA(dst, b, h) do { _Pragma("unroll") for (int m = 0; m < 4; ++m) _Pragma("unroll") for (int k = 0; k < 2; ++k) dst[m][k] = *(const LAS bf16x8*)(lds + PG8_SA(b, h) + aoff + m * 2048 + k * 1024); } while (0)
; #define PG8_LDB(dst, b, h) do { _Pragma("unroll") for (int n = 0; n < 2; ++n) _Pragma("unroll") for (int k = 0; k < 2; ++k) dst[n][k] = *(const LAS bf16x8*)(lds + PG8_SB(b, h) + boff + n * 2048 + k * 1024); } while (0)
; #define PG8_MMA(ai, bj, At, Bt) do { __builtin_amdgcn_s_setprio(1); _Pragma("unroll") for (int m = 0; m < 4; ++m) _Pragma("unroll") for (int n = 0; n < 2; ++n) _Pragma("unroll") for (int k = 0; k < 2; ++k) \
;         acc[ai][bj][m][n] = __builtin_amdgcn_mfma_f32_16x16x32_bf16(Bt[n][k], At[m][k], acc[ai][bj][m][n], 0, 0, 0); __builtin_amdgcn_s_setprio(0); } while (0)
; #define PG8_BAR __builtin_amdgcn_s_barrier()
; template <class Epi, bool ALIGN_EPI = true, bool SP2 = true>
; DI void gemm_phase(LAS unsigned char* lds, const Gemm g, const StaticOrder& S, const Epi& E) {
;     ...
;             const bool last = (t == nt - 2);
;             const char* a1 = cA + (size_t)(t + 1) * kstep;
;             const char* a2 = last ? nA : cA + (size_t)(t + 2) * kstep; const char* b2 = last ? nB : cB + (size_t)(t + 2) * kstep;
;             const char* a3 = a2 + kstep; const char* b3 = b2 + kstep;
;             if (Epi::MID) { if (t == (nt >> 1)) {
;                 if constexpr (ALIGN_EPI) { if (wr == 0) PG8_BAR; }
;                 E.mid(acc, cur, wr, wc, fr, fq);
;                 if constexpr (ALIGN_EPI) { if (wr == 1) PG8_BAR; } } }
;             if constexpr (SP2) {
;             PG8_LDB(B0, 0, 0); PG8_LDB(B1, 0, 1); PG8_SCHED; PG8_LDA(At, 0, 0); PG8_STAGE(PG8_SA(1, 1), a1 + hstepA, voffA);
;             PG8_WAIT_V(8); PG8_WAIT_L(0); PG8_BAR; PG8_MMA(0, 0, At, B0); PG8_MMA(0, 1, At, B1); PG8_BAR; PG8_SCHED;
;             PG8_LDA(At, 0, 1); PG8_STAGE(PG8_SB(0, 0), b2, voffB); PG8_STAGE(PG8_SB(0, 1), b2 + hstepB, voffB); PG8_STAGE(PG8_SA(0, 0), a2, voffA);
;             PG8_WAIT_V(8); PG8_WAIT_L(0); PG8_BAR; PG8_MMA(1, 0, At, B0); PG8_MMA(1, 1, At, B1); PG8_BAR; PG8_SCHED;
.LBB0_755:
	v_add_u32_e32 v1, s67, v227
	ds_read_b128 v[132:135], v1
	ds_read_b128 v[136:139], v1 offset:1024
	ds_read_b128 v[140:143], v1 offset:2048
	ds_read_b128 v[144:147], v1 offset:3072
	v_add_u32_e32 v1, s68, v227
	s_add_u32 s8, s26, s30
	ds_read_b128 v[148:151], v1
	ds_read_b128 v[152:155], v1 offset:1024
	ds_read_b128 v[156:159], v1 offset:2048
	ds_read_b128 v[160:163], v1 offset:3072
	s_addc_u32 s9, s27, s31
	s_add_u32 s8, s8, 0x100
	s_addc_u32 s9, s9, 0
	s_add_u32 s34, s73, s30
	s_addc_u32 s35, s74, s31
	s_cmpk_eq_i32 s30, 0x1f00
	s_cselect_b32 s37, s21, s9
	s_cselect_b32 s36, s69, s8
	s_cselect_b32 s35, s70, s35
	s_cselect_b32 s34, s71, s34
	v_lshl_add_u64 v[2:3], v[188:189], 0, s[30:31]
	s_add_i32 m0, s43, 0xc000
	ds_read_b128 v[164:167], v229
	ds_read_b128 v[168:171], v229 offset:1024
	ds_read_b128 v[172:175], v229 offset:2048
	ds_read_b128 v[176:179], v229 offset:3072
	ds_read_b128 v[180:183], v229 offset:4096
	ds_read_b128 v[184:187], v229 offset:5120
	ds_read_b128 v[212:215], v229 offset:6144
	ds_read_b128 v[216:219], v229 offset:7168
	global_load_lds_dwordx4 v[2:3], off
	v_lshl_add_u64 v[2:3], v[190:191], 0, s[30:31]
	s_add_i32 m0, s43, 0xe000
	s_nop 0
	global_load_lds_dwordx4 v[2:3], off
	s_waitcnt vmcnt(8)
	s_waitcnt lgkmcnt(0)
	s_barrier
	v_mfma_f32_16x16x32_bf16 v[128:131], v[132:135], v[164:167], v[128:131]
	v_mfma_f32_16x16x32_bf16 v[124:127], v[140:143], v[164:167], v[124:127]
	v_mfma_f32_16x16x32_bf16 v[112:115], v[132:135], v[172:175], v[112:115]
	v_mfma_f32_16x16x32_bf16 v[108:111], v[140:143], v[172:175], v[108:111]
	v_mfma_f32_16x16x32_bf16 v[96:99], v[132:135], v[180:183], v[96:99]
	v_mfma_f32_16x16x32_bf16 v[92:95], v[140:143], v[180:183], v[92:95]
	v_mfma_f32_16x16x32_bf16 v[80:83], v[132:135], v[212:215], v[80:83]
	v_mfma_f32_16x16x32_bf16 v[76:79], v[140:143], v[212:215], v[76:79]
	v_mfma_f32_16x16x32_bf16 v[128:131], v[136:139], v[168:171], v[128:131]
	v_mfma_f32_16x16x32_bf16 v[124:127], v[144:147], v[168:171], v[124:127]
	v_mfma_f32_16x16x32_bf16 v[112:115], v[136:139], v[176:179], v[112:115]
	v_mfma_f32_16x16x32_bf16 v[108:111], v[144:147], v[176:179], v[108:111]
	v_mfma_f32_16x16x32_bf16 v[96:99], v[136:139], v[184:187], v[96:99]
	v_mfma_f32_16x16x32_bf16 v[92:95], v[144:147], v[184:187], v[92:95]
	v_mfma_f32_16x16x32_bf16 v[80:83], v[136:139], v[216:219], v[80:83]
	v_mfma_f32_16x16x32_bf16 v[76:79], v[144:147], v[216:219], v[76:79]
	v_mfma_f32_16x16x32_bf16 v[120:123], v[148:151], v[164:167], v[120:123]
	v_mfma_f32_16x16x32_bf16 v[116:119], v[156:159], v[164:167], v[116:119]
	v_mfma_f32_16x16x32_bf16 v[104:107], v[148:151], v[172:175], v[104:107]
	v_mfma_f32_16x16x32_bf16 v[100:103], v[156:159], v[172:175], v[100:103]
	v_mfma_f32_16x16x32_bf16 v[88:91], v[148:151], v[180:183], v[88:91]
	v_mfma_f32_16x16x32_bf16 v[84:87], v[156:159], v[180:183], v[84:87]
	v_mfma_f32_16x16x32_bf16 v[72:75], v[148:151], v[212:215], v[72:75]
	v_mfma_f32_16x16x32_bf16 v[68:71], v[156:159], v[212:215], v[68:71]
	v_mfma_f32_16x16x32_bf16 v[120:123], v[152:155], v[168:171], v[120:123]
	v_mfma_f32_16x16x32_bf16 v[116:119], v[160:163], v[168:171], v[116:119]
	v_mfma_f32_16x16x32_bf16 v[104:107], v[152:155], v[176:179], v[104:107]
	v_mfma_f32_16x16x32_bf16 v[100:103], v[160:163], v[176:179], v[100:103]
	v_mfma_f32_16x16x32_bf16 v[88:91], v[152:155], v[184:187], v[88:91]
	v_mfma_f32_16x16x32_bf16 v[84:87], v[160:163], v[184:187], v[84:87]
	v_mfma_f32_16x16x32_bf16 v[72:75], v[152:155], v[216:219], v[72:75]
	v_mfma_f32_16x16x32_bf16 v[68:71], v[160:163], v[216:219], v[68:71]
	s_barrier
	s_add_i32 s8, s67, s42
	v_lshl_add_u64 v[220:221], s[34:35], 0, v[194:195]
	s_mov_b32 m0, s8
	ds_read_b128 v[164:167], v229 offset:16384
	ds_read_b128 v[168:171], v229 offset:17408
	ds_read_b128 v[172:175], v229 offset:18432
	ds_read_b128 v[176:179], v229 offset:19456
	ds_read_b128 v[180:183], v229 offset:20480
	ds_read_b128 v[184:187], v229 offset:21504
	ds_read_b128 v[212:215], v229 offset:22528
	ds_read_b128 v[216:219], v229 offset:23552
	global_load_lds_dwordx4 v[220:221], off
	s_add_i32 m0, s8, 0x2000
	s_add_u32 s76, s34, 0x100000
	v_lshl_add_u64 v[222:223], s[34:35], 0, v[198:199]
	s_addc_u32 s77, s35, 0
	s_add_i32 s8, s68, s42
	global_load_lds_dwordx4 v[222:223], off
	v_lshl_add_u64 v[2:3], s[76:77], 0, v[194:195]
	s_mov_b32 m0, s8
	v_lshl_add_u64 v[232:233], s[36:37], 0, v[192:193]
	global_load_lds_dwordx4 v[2:3], off
	v_lshl_add_u64 v[2:3], s[76:77], 0, v[198:199]
	s_add_i32 m0, s8, 0x2000
	v_lshl_add_u64 v[234:235], s[36:37], 0, v[196:197]
	global_load_lds_dwordx4 v[2:3], off
	s_mov_b32 m0, s43
	s_nop 0
	global_load_lds_dwordx4 v[232:233], off
	s_mov_b32 m0, s44
	s_nop 0
	global_load_lds_dwordx4 v[234:235], off
	s_waitcnt vmcnt(8)
	s_waitcnt lgkmcnt(0)
	s_barrier
; #define PG8_STAGE(bufoff, gbase, voff) do { _Pragma("unroll") for (int _i = 0; _i < 2; ++_i) \
;         __builtin_amdgcn_global_load_lds((const unsigned*)((const char*)(gbase) + (voff)[_i]), (LAS unsigned*)(lds + (bufoff) + ldsw + _i * 8192), 16, 0, 0); } while (0)
; #define PG8_LDA(dst, b, h) do { _Pragma("unroll") for (int m = 0; m < 4; ++m) _Pragma("unroll") for (int k = 0; k < 2; ++k) dst[m][k] = *(const LAS bf16x8*)(lds + PG8_SA(b, h) + aoff + m * 2048 + k * 1024); } while (0)
; #define PG8_LDB(dst, b, h) do { _Pragma("unroll") for (int n = 0; n < 2; ++n) _Pragma("unroll") for (int k = 0; k < 2; ++k) dst[n][k] = *(const LAS bf16x8*)(lds + PG8_SB(b, h) + boff + n * 2048 + k * 1024); } while (0)
; #define PG8_MMA(ai, bj, At, Bt) do { __builtin_amdgcn_s_setprio(1); _Pragma("unroll") for (int m = 0; m < 4; ++m) _Pragma("unroll") for (int n = 0; n < 2; ++n) _Pragma("unroll") for (int k = 0; k < 2; ++k) \
;         acc[ai][bj][m][n] = __builtin_amdgcn_mfma_f32_16x16x32_bf16(Bt[n][k], At[m][k], acc[ai][bj][m][n], 0, 0, 0); __builtin_amdgcn_s_setprio(0); } while (0)
; #define PG8_WAIT_V(n) asm volatile("s_waitcnt vmcnt(" #n ")" ::: "memory")
; #define PG8_WAIT_L(n) asm volatile("s_waitcnt lgkmcnt(" #n ")" ::: "memory")
; #define PG8_BAR __builtin_amdgcn_s_barrier()
; #define PG8_SCHED __builtin_amdgcn_sched_barrier(0)
; template <class Epi, bool ALIGN_EPI = true, bool SP2 = true>
; DI void gemm_phase(LAS unsigned char* lds, const Gemm g, const StaticOrder& S, const Epi& E) {
;     ...
;             PG8_WAIT_V(8); PG8_WAIT_L(0); PG8_BAR; PG8_MMA(1, 0, At, B0); PG8_MMA(1, 1, At, B1); PG8_BAR; PG8_SCHED;
;             PG8_LDB(B0, 1, 0); PG8_LDB(B1, 1, 1); PG8_SCHED; PG8_LDA(At, 1, 0); PG8_STAGE(PG8_SA(0, 1), a2 + hstepA, voffA);
;             PG8_WAIT_V(8); PG8_WAIT_L(0); PG8_BAR; PG8_MMA(0, 0, At, B0); PG8_MMA(0, 1, At, B1); PG8_BAR; PG8_SCHED;
	v_mfma_f32_16x16x32_bf16 v[64:67], v[132:135], v[164:167], v[64:67]
	v_mfma_f32_16x16x32_bf16 v[60:63], v[140:143], v[164:167], v[60:63]
	v_mfma_f32_16x16x32_bf16 v[48:51], v[132:135], v[172:175], v[48:51]
	v_mfma_f32_16x16x32_bf16 v[44:47], v[140:143], v[172:175], v[44:47]
	v_mfma_f32_16x16x32_bf16 v[32:35], v[132:135], v[180:183], v[32:35]
	v_mfma_f32_16x16x32_bf16 v[28:31], v[140:143], v[180:183], v[28:31]
	v_mfma_f32_16x16x32_bf16 v[16:19], v[132:135], v[212:215], v[16:19]
	v_mfma_f32_16x16x32_bf16 v[12:15], v[140:143], v[212:215], v[12:15]
	v_mfma_f32_16x16x32_bf16 v[64:67], v[136:139], v[168:171], v[64:67]
	v_mfma_f32_16x16x32_bf16 v[60:63], v[144:147], v[168:171], v[60:63]
	v_mfma_f32_16x16x32_bf16 v[48:51], v[136:139], v[176:179], v[48:51]
	v_mfma_f32_16x16x32_bf16 v[44:47], v[144:147], v[176:179], v[44:47]
	v_mfma_f32_16x16x32_bf16 v[32:35], v[136:139], v[184:187], v[32:35]
	v_mfma_f32_16x16x32_bf16 v[28:31], v[144:147], v[184:187], v[28:31]
	v_mfma_f32_16x16x32_bf16 v[16:19], v[136:139], v[216:219], v[16:19]
	v_mfma_f32_16x16x32_bf16 v[12:15], v[144:147], v[216:219], v[12:15]
	v_mfma_f32_16x16x32_bf16 v[56:59], v[148:151], v[164:167], v[56:59]
	v_mfma_f32_16x16x32_bf16 v[52:55], v[156:159], v[164:167], v[52:55]
	v_mfma_f32_16x16x32_bf16 v[40:43], v[148:151], v[172:175], v[40:43]
	v_mfma_f32_16x16x32_bf16 v[36:39], v[156:159], v[172:175], v[36:39]
	v_mfma_f32_16x16x32_bf16 v[24:27], v[148:151], v[180:183], v[24:27]
	v_mfma_f32_16x16x32_bf16 v[20:23], v[156:159], v[180:183], v[20:23]
	v_mfma_f32_16x16x32_bf16 v[8:11], v[148:151], v[212:215], v[8:11]
	v_mfma_f32_16x16x32_bf16 v[2:5], v[156:159], v[212:215], v[4:7]
	v_mfma_f32_16x16x32_bf16 v[56:59], v[152:155], v[168:171], v[56:59]
	v_mfma_f32_16x16x32_bf16 v[52:55], v[160:163], v[168:171], v[52:55]
	v_mfma_f32_16x16x32_bf16 v[40:43], v[152:155], v[176:179], v[40:43]
	v_mfma_f32_16x16x32_bf16 v[36:39], v[160:163], v[176:179], v[36:39]
	v_mfma_f32_16x16x32_bf16 v[24:27], v[152:155], v[184:187], v[24:27]
	v_mfma_f32_16x16x32_bf16 v[20:23], v[160:163], v[184:187], v[20:23]
	v_mfma_f32_16x16x32_bf16 v[8:11], v[152:155], v[216:219], v[8:11]
	v_mfma_f32_16x16x32_bf16 v[2:5], v[160:163], v[216:219], v[2:5]
	s_barrier
	s_add_i32 s8, 0, 0x18000
	v_add_u32_e32 v1, s8, v227
	s_add_i32 s9, 0, 0x1c000
	ds_read_b128 v[132:135], v1
	ds_read_b128 v[136:139], v1 offset:1024
	ds_read_b128 v[140:143], v1 offset:2048
	ds_read_b128 v[144:147], v1 offset:3072
	v_add_u32_e32 v1, s9, v227
	ds_read_b128 v[148:151], v1
	ds_read_b128 v[152:155], v1 offset:1024
	ds_read_b128 v[156:159], v1 offset:2048
	ds_read_b128 v[160:163], v1 offset:3072
	s_add_u32 s36, s36, 0x100000
	s_addc_u32 s37, s37, 0
	s_mov_b32 m0, s45
	v_lshl_add_u64 v[6:7], s[36:37], 0, v[192:193]
	ds_read_b128 v[164:167], v229 offset:32768
	ds_read_b128 v[168:171], v229 offset:33792
	ds_read_b128 v[172:175], v229 offset:34816
	ds_read_b128 v[176:179], v229 offset:35840
	ds_read_b128 v[180:183], v229 offset:36864
	ds_read_b128 v[184:187], v229 offset:37888
	ds_read_b128 v[212:215], v229 offset:38912
	ds_read_b128 v[216:219], v229 offset:39936
	global_load_lds_dwordx4 v[6:7], off
	v_lshl_add_u64 v[6:7], s[36:37], 0, v[196:197]
	s_mov_b32 m0, s46
	s_nop 0
	global_load_lds_dwordx4 v[6:7], off
	s_waitcnt vmcnt(8)
	s_waitcnt lgkmcnt(0)
	s_barrier
	v_mfma_f32_16x16x32_bf16 v[128:131], v[132:135], v[164:167], v[128:131]
	v_mfma_f32_16x16x32_bf16 v[124:127], v[140:143], v[164:167], v[124:127]
	v_mfma_f32_16x16x32_bf16 v[112:115], v[132:135], v[172:175], v[112:115]
	v_mfma_f32_16x16x32_bf16 v[108:111], v[140:143], v[172:175], v[108:111]
	v_mfma_f32_16x16x32_bf16 v[96:99], v[132:135], v[180:183], v[96:99]
	v_mfma_f32_16x16x32_bf16 v[92:95], v[140:143], v[180:183], v[92:95]
	v_mfma_f32_16x16x32_bf16 v[80:83], v[132:135], v[212:215], v[80:83]
	v_mfma_f32_16x16x32_bf16 v[76:79], v[140:143], v[212:215], v[76:79]
	v_mfma_f32_16x16x32_bf16 v[128:131], v[136:139], v[168:171], v[128:131]
	v_mfma_f32_16x16x32_bf16 v[124:127], v[144:147], v[168:171], v[124:127]
	v_mfma_f32_16x16x32_bf16 v[112:115], v[136:139], v[176:179], v[112:115]
	v_mfma_f32_16x16x32_bf16 v[108:111], v[144:147], v[176:179], v[108:111]
	v_mfma_f32_16x16x32_bf16 v[96:99], v[136:139], v[184:187], v[96:99]
	v_mfma_f32_16x16x32_bf16 v[92:95], v[144:147], v[184:187], v[92:95]
	v_mfma_f32_16x16x32_bf16 v[80:83], v[136:139], v[216:219], v[80:83]
	v_mfma_f32_16x16x32_bf16 v[76:79], v[144:147], v[216:219], v[76:79]
	v_mfma_f32_16x16x32_bf16 v[120:123], v[148:151], v[164:167], v[120:123]
	v_mfma_f32_16x16x32_bf16 v[116:119], v[156:159], v[164:167], v[116:119]
	v_mfma_f32_16x16x32_bf16 v[104:107], v[148:151], v[172:175], v[104:107]
	v_mfma_f32_16x16x32_bf16 v[100:103], v[156:159], v[172:175], v[100:103]
	v_mfma_f32_16x16x32_bf16 v[88:91], v[148:151], v[180:183], v[88:91]
	v_mfma_f32_16x16x32_bf16 v[84:87], v[156:159], v[180:183], v[84:87]
	v_mfma_f32_16x16x32_bf16 v[72:75], v[148:151], v[212:215], v[72:75]
	v_mfma_f32_16x16x32_bf16 v[68:71], v[156:159], v[212:215], v[68:71]
	v_mfma_f32_16x16x32_bf16 v[120:123], v[152:155], v[168:171], v[120:123]
	v_mfma_f32_16x16x32_bf16 v[116:119], v[160:163], v[168:171], v[116:119]
	v_mfma_f32_16x16x32_bf16 v[104:107], v[152:155], v[176:179], v[104:107]
	v_mfma_f32_16x16x32_bf16 v[100:103], v[160:163], v[176:179], v[100:103]
	v_mfma_f32_16x16x32_bf16 v[88:91], v[152:155], v[184:187], v[88:91]
	v_mfma_f32_16x16x32_bf16 v[84:87], v[160:163], v[184:187], v[84:87]
	v_mfma_f32_16x16x32_bf16 v[72:75], v[152:155], v[216:219], v[72:75]
	v_mfma_f32_16x16x32_bf16 v[68:71], v[160:163], v[216:219], v[68:71]
	s_barrier
; #define PG8_STAGE(bufoff, gbase, voff) do { _Pragma("unroll") for (int _i = 0; _i < 2; ++_i) \
;         __builtin_amdgcn_global_load_lds((const unsigned*)((const char*)(gbase) + (voff)[_i]), (LAS unsigned*)(lds + (bufoff) + ldsw + _i * 8192), 16, 0, 0); } while (0)
; #define PG8_LDA(dst, b, h) do { _Pragma("unroll") for (int m = 0; m < 4; ++m) _Pragma("unroll") for (int k = 0; k < 2; ++k) dst[m][k] = *(const LAS bf16x8*)(lds + PG8_SA(b, h) + aoff + m * 2048 + k * 1024); } while (0)
; #define PG8_MMA(ai, bj, At, Bt) do { __builtin_amdgcn_s_setprio(1); _Pragma("unroll") for (int m = 0; m < 4; ++m) _Pragma("unroll") for (int n = 0; n < 2; ++n) _Pragma("unroll") for (int k = 0; k < 2; ++k) \
;         acc[ai][bj][m][n] = __builtin_amdgcn_mfma_f32_16x16x32_bf16(Bt[n][k], At[m][k], acc[ai][bj][m][n], 0, 0, 0); __builtin_amdgcn_s_setprio(0); } while (0)
; #define PG8_WAIT_V(n) asm volatile("s_waitcnt vmcnt(" #n ")" ::: "memory")
; #define PG8_WAIT_L(n) asm volatile("s_waitcnt lgkmcnt(" #n ")" ::: "memory")
; #define PG8_BAR __builtin_amdgcn_s_barrier()
; #define PG8_SCHED __builtin_amdgcn_sched_barrier(0)
; template <class Epi, bool ALIGN_EPI = true, bool SP2 = true>
; DI void gemm_phase(LAS unsigned char* lds, const Gemm g, const StaticOrder& S, const Epi& E) {
;     ...
;             PG8_LDA(At, 1, 1); PG8_STAGE(PG8_SB(1, 0), b3, voffB); PG8_STAGE(PG8_SB(1, 1), b3 + hstepB, voffB); PG8_STAGE(PG8_SA(1, 0), a3, voffA);
;             PG8_WAIT_V(8); PG8_WAIT_L(0); PG8_BAR; PG8_MMA(1, 0, At, B0); PG8_MMA(1, 1, At, B1); PG8_BAR; PG8_SCHED;
	s_add_i32 s8, s8, s42
	v_lshl_add_u64 v[6:7], v[220:221], 0, s[10:11]
	s_mov_b32 m0, s8
	ds_read_b128 v[164:167], v229 offset:49152
	ds_read_b128 v[168:171], v229 offset:50176
	ds_read_b128 v[172:175], v229 offset:51200
	ds_read_b128 v[176:179], v229 offset:52224
	ds_read_b128 v[180:183], v229 offset:53248
	ds_read_b128 v[184:187], v229 offset:54272
	ds_read_b128 v[212:215], v229 offset:55296
	ds_read_b128 v[216:219], v229 offset:56320
	global_load_lds_dwordx4 v[6:7], off
	s_add_i32 m0, s8, 0x2000
	s_add_u32 s34, s34, 0x100080
	v_lshl_add_u64 v[6:7], v[222:223], 0, s[10:11]
	s_addc_u32 s35, s35, 0
	s_add_i32 s8, s9, s42
	global_load_lds_dwordx4 v[6:7], off
	v_lshl_add_u64 v[6:7], s[34:35], 0, v[194:195]
	s_mov_b32 m0, s8
	s_nop 0
	global_load_lds_dwordx4 v[6:7], off
	v_lshl_add_u64 v[6:7], s[34:35], 0, v[198:199]
	s_add_i32 m0, s8, 0x2000
	s_nop 0
	global_load_lds_dwordx4 v[6:7], off
	v_lshl_add_u64 v[6:7], v[232:233], 0, s[10:11]
	s_mov_b32 m0, s51
	s_nop 0
	global_load_lds_dwordx4 v[6:7], off
	v_lshl_add_u64 v[6:7], v[234:235], 0, s[10:11]
	s_mov_b32 m0, s60
	s_nop 0
	global_load_lds_dwordx4 v[6:7], off
	s_waitcnt vmcnt(8)
	s_waitcnt lgkmcnt(0)
	s_barrier
	v_mfma_f32_16x16x32_bf16 v[64:67], v[132:135], v[164:167], v[64:67]
	v_mfma_f32_16x16x32_bf16 v[60:63], v[140:143], v[164:167], v[60:63]
	v_mfma_f32_16x16x32_bf16 v[48:51], v[132:135], v[172:175], v[48:51]
	v_mfma_f32_16x16x32_bf16 v[44:47], v[140:143], v[172:175], v[44:47]
	v_mfma_f32_16x16x32_bf16 v[32:35], v[132:135], v[180:183], v[32:35]
	v_mfma_f32_16x16x32_bf16 v[28:31], v[140:143], v[180:183], v[28:31]
	v_mfma_f32_16x16x32_bf16 v[16:19], v[132:135], v[212:215], v[16:19]
	v_mfma_f32_16x16x32_bf16 v[12:15], v[140:143], v[212:215], v[12:15]
	v_mfma_f32_16x16x32_bf16 v[64:67], v[136:139], v[168:171], v[64:67]
	v_mfma_f32_16x16x32_bf16 v[60:63], v[144:147], v[168:171], v[60:63]
	v_mfma_f32_16x16x32_bf16 v[48:51], v[136:139], v[176:179], v[48:51]
	v_mfma_f32_16x16x32_bf16 v[44:47], v[144:147], v[176:179], v[44:47]
	v_mfma_f32_16x16x32_bf16 v[32:35], v[136:139], v[184:187], v[32:35]
	v_mfma_f32_16x16x32_bf16 v[28:31], v[144:147], v[184:187], v[28:31]
	v_mfma_f32_16x16x32_bf16 v[16:19], v[136:139], v[216:219], v[16:19]
	v_mfma_f32_16x16x32_bf16 v[12:15], v[144:147], v[216:219], v[12:15]
	v_mfma_f32_16x16x32_bf16 v[56:59], v[148:151], v[164:167], v[56:59]
	v_mfma_f32_16x16x32_bf16 v[52:55], v[156:159], v[164:167], v[52:55]
	v_mfma_f32_16x16x32_bf16 v[40:43], v[148:151], v[172:175], v[40:43]
	v_mfma_f32_16x16x32_bf16 v[36:39], v[156:159], v[172:175], v[36:39]
	v_mfma_f32_16x16x32_bf16 v[24:27], v[148:151], v[180:183], v[24:27]
	v_mfma_f32_16x16x32_bf16 v[20:23], v[156:159], v[180:183], v[20:23]
	v_mfma_f32_16x16x32_bf16 v[6:9], v[148:151], v[212:215], v[8:11]
	v_mfma_f32_16x16x32_bf16 v[2:5], v[156:159], v[212:215], v[2:5]
	v_mfma_f32_16x16x32_bf16 v[56:59], v[152:155], v[168:171], v[56:59]
	v_mfma_f32_16x16x32_bf16 v[52:55], v[160:163], v[168:171], v[52:55]
	v_mfma_f32_16x16x32_bf16 v[40:43], v[152:155], v[176:179], v[40:43]
	v_mfma_f32_16x16x32_bf16 v[36:39], v[160:163], v[176:179], v[36:39]
	v_mfma_f32_16x16x32_bf16 v[24:27], v[152:155], v[184:187], v[24:27]
	v_mfma_f32_16x16x32_bf16 v[20:23], v[160:163], v[184:187], v[20:23]
	v_mfma_f32_16x16x32_bf16 v[8:11], v[152:155], v[216:219], v[6:9]
	v_mfma_f32_16x16x32_bf16 v[4:7], v[160:163], v[216:219], v[2:5]
	s_barrier
	s_add_i32 s75, s75, 2
	s_add_u32 s30, s30, 0x100
	s_addc_u32 s31, s31, 0
	s_cmp_gt_u32 s75, 61
	s_cbranch_scc1 .LBB0_761

; #define PG8_STAGE(bufoff, gbase, voff) do { _Pragma("unroll") for (int _i = 0; _i < 2; ++_i) \
;         __builtin_amdgcn_global_load_lds((const unsigned*)((const char*)(gbase) + (voff)[_i]), (LAS unsigned*)(lds + (bufoff) + ldsw + _i * 8192), 16, 0, 0); } while (0)
; #define PG8_LDA(dst, b, h) do { _Pragma("unroll") for (int m = 0; m < 4; ++m) _Pragma("unroll") for (int k = 0; k < 2; ++k) dst[m][k] = *(const LAS bf16x8*)(lds + PG8_SA(b, h) + aoff + m * 2048 + k * 1024); } while (0)
; #define PG8_LDB(dst, b, h) do { _Pragma("unroll") for (int n = 0; n < 2; ++n) _Pragma("unroll") for (int k = 0; k < 2; ++k) dst[n][k] = *(const LAS bf16x8*)(lds + PG8_SB(b, h) + boff + n * 2048 + k * 1024); } while (0)
; #define PG8_MMA(ai, bj, At, Bt) do { __builtin_amdgcn_s_setprio(1); _Pragma("unroll") for (int m = 0; m < 4; ++m) _Pragma("unroll") for (int n = 0; n < 2; ++n) _Pragma("unroll") for (int k = 0; k < 2; ++k) \
;         acc[ai][bj][m][n] = __builtin_amdgcn_mfma_f32_16x16x32_bf16(Bt[n][k], At[m][k], acc[ai][bj][m][n], 0, 0, 0); __builtin_amdgcn_s_setprio(0); } while (0)
; #define PG8_BAR __builtin_amdgcn_s_barrier()
; template <class Epi, bool ALIGN_EPI = true, bool SP2 = true>
; DI void gemm_phase(LAS unsigned char* lds, const Gemm g, const StaticOrder& S, const Epi& E) {
;     ...
;             const bool last = (t == nt - 2);
;             const char* a1 = cA + (size_t)(t + 1) * kstep;
;             const char* a2 = last ? nA : cA + (size_t)(t + 2) * kstep; const char* b2 = last ? nB : cB + (size_t)(t + 2) * kstep;
;             const char* a3 = a2 + kstep; const char* b3 = b2 + kstep;
;             if (Epi::MID) { if (t == (nt >> 1)) {
;                 if constexpr (ALIGN_EPI) { if (wr == 0) PG8_BAR; }
;                 E.mid(acc, cur, wr, wc, fr, fq);
;                 if constexpr (ALIGN_EPI) { if (wr == 1) PG8_BAR; } } }
;             if constexpr (SP2) {
;             PG8_LDB(B0, 0, 0); PG8_LDB(B1, 0, 1); PG8_SCHED; PG8_LDA(At, 0, 0); PG8_STAGE(PG8_SA(1, 1), a1 + hstepA, voffA);
;             PG8_WAIT_V(8); PG8_WAIT_L(0); PG8_BAR; PG8_MMA(0, 0, At, B0); PG8_MMA(0, 1, At, B1); PG8_BAR; PG8_SCHED;
;             PG8_LDA(At, 0, 1); PG8_STAGE(PG8_SB(0, 0), b2, voffB); PG8_STAGE(PG8_SB(0, 1), b2 + hstepB, voffB); PG8_STAGE(PG8_SA(0, 0), a2, voffA);
;             PG8_WAIT_V(8); PG8_WAIT_L(0); PG8_BAR; PG8_MMA(1, 0, At, B0); PG8_MMA(1, 1, At, B1); PG8_BAR; PG8_SCHED;
.LBB0_839:
	ds_read_b128 v[140:143], v149
	ds_read_b128 v[152:155], v149 offset:1024
	ds_read_b128 v[156:159], v149 offset:2048
	ds_read_b128 v[160:163], v149 offset:3072
	ds_read_b128 v[164:167], v150
	ds_read_b128 v[168:171], v150 offset:1024
	ds_read_b128 v[172:175], v150 offset:2048
	ds_read_b128 v[176:179], v150 offset:3072
	s_add_u32 s34, s30, 0xfff00080
	s_addc_u32 s35, s31, -1
	s_cmp_eq_u32 s59, 60
	s_cselect_b32 s37, s23, s35
	s_cselect_b32 s36, s50, s34
	s_cselect_b32 s35, s21, s57
	s_cselect_b32 s34, s51, s56
	v_lshl_add_u64 v[144:145], s[30:31], 0, v[132:133]
	s_add_i32 m0, s29, 0xc000
	ds_read_b128 v[180:183], v151
	ds_read_b128 v[184:187], v151 offset:1024
	ds_read_b128 v[188:191], v151 offset:2048
	ds_read_b128 v[192:195], v151 offset:3072
	ds_read_b128 v[196:199], v151 offset:4096
	ds_read_b128 v[200:203], v151 offset:5120
	ds_read_b128 v[204:207], v151 offset:6144
	ds_read_b128 v[208:211], v151 offset:7168
	global_load_lds_dwordx4 v[144:145], off
	v_lshl_add_u64 v[144:145], s[30:31], 0, v[134:135]
	s_add_i32 m0, s29, 0xe000
	s_nop 0
	global_load_lds_dwordx4 v[144:145], off
	s_waitcnt vmcnt(8)
	s_waitcnt lgkmcnt(0)
	s_barrier
	v_mfma_f32_16x16x32_bf16 v[124:127], v[140:143], v[180:183], v[124:127]
	v_mfma_f32_16x16x32_bf16 v[120:123], v[156:159], v[180:183], v[120:123]
	v_mfma_f32_16x16x32_bf16 v[116:119], v[140:143], v[188:191], v[116:119]
	v_mfma_f32_16x16x32_bf16 v[112:115], v[156:159], v[188:191], v[112:115]
	v_mfma_f32_16x16x32_bf16 v[108:111], v[140:143], v[196:199], v[108:111]
	v_mfma_f32_16x16x32_bf16 v[100:103], v[156:159], v[196:199], v[100:103]
	v_mfma_f32_16x16x32_bf16 v[92:95], v[140:143], v[204:207], v[92:95]
	v_mfma_f32_16x16x32_bf16 v[80:83], v[156:159], v[204:207], v[80:83]
	v_mfma_f32_16x16x32_bf16 v[124:127], v[152:155], v[184:187], v[124:127]
	v_mfma_f32_16x16x32_bf16 v[120:123], v[160:163], v[184:187], v[120:123]
	v_mfma_f32_16x16x32_bf16 v[116:119], v[152:155], v[192:195], v[116:119]
	v_mfma_f32_16x16x32_bf16 v[112:115], v[160:163], v[192:195], v[112:115]
	v_mfma_f32_16x16x32_bf16 v[108:111], v[152:155], v[200:203], v[108:111]
	v_mfma_f32_16x16x32_bf16 v[100:103], v[160:163], v[200:203], v[100:103]
	v_mfma_f32_16x16x32_bf16 v[92:95], v[152:155], v[208:211], v[92:95]
	v_mfma_f32_16x16x32_bf16 v[80:83], v[160:163], v[208:211], v[80:83]
	v_mfma_f32_16x16x32_bf16 v[104:107], v[164:167], v[180:183], v[104:107]
	v_mfma_f32_16x16x32_bf16 v[96:99], v[172:175], v[180:183], v[96:99]
	v_mfma_f32_16x16x32_bf16 v[88:91], v[164:167], v[188:191], v[88:91]
	v_mfma_f32_16x16x32_bf16 v[84:87], v[172:175], v[188:191], v[84:87]
	v_mfma_f32_16x16x32_bf16 v[76:79], v[164:167], v[196:199], v[76:79]
	v_mfma_f32_16x16x32_bf16 v[72:75], v[172:175], v[196:199], v[72:75]
	v_mfma_f32_16x16x32_bf16 v[68:71], v[164:167], v[204:207], v[68:71]
	v_mfma_f32_16x16x32_bf16 v[64:67], v[172:175], v[204:207], v[64:67]
	v_mfma_f32_16x16x32_bf16 v[104:107], v[168:171], v[184:187], v[104:107]
	v_mfma_f32_16x16x32_bf16 v[96:99], v[176:179], v[184:187], v[96:99]
	v_mfma_f32_16x16x32_bf16 v[88:91], v[168:171], v[192:195], v[88:91]
	v_mfma_f32_16x16x32_bf16 v[84:87], v[176:179], v[192:195], v[84:87]
	v_mfma_f32_16x16x32_bf16 v[76:79], v[168:171], v[200:203], v[76:79]
	v_mfma_f32_16x16x32_bf16 v[72:75], v[176:179], v[200:203], v[72:75]
	v_mfma_f32_16x16x32_bf16 v[68:71], v[168:171], v[208:211], v[68:71]
	v_mfma_f32_16x16x32_bf16 v[64:67], v[176:179], v[208:211], v[64:67]
	s_barrier
	s_add_i32 s60, s47, s39
	v_lshl_add_u64 v[144:145], s[34:35], 0, v[128:129]
	s_mov_b32 m0, s60
	ds_read_b128 v[180:183], v151 offset:16384
	ds_read_b128 v[184:187], v151 offset:17408
	ds_read_b128 v[188:191], v151 offset:18432
	ds_read_b128 v[192:195], v151 offset:19456
	ds_read_b128 v[196:199], v151 offset:20480
	ds_read_b128 v[200:203], v151 offset:21504
	ds_read_b128 v[204:207], v151 offset:22528
	ds_read_b128 v[208:211], v151 offset:23552
	global_load_lds_dwordx4 v[144:145], off
	s_add_i32 m0, s60, 0x2000
	s_add_u32 s60, s34, 0x100000
	v_lshl_add_u64 v[212:213], s[34:35], 0, v[130:131]
	s_addc_u32 s61, s35, 0
	s_add_i32 s62, s48, s39
	global_load_lds_dwordx4 v[212:213], off
	v_lshl_add_u64 v[214:215], s[60:61], 0, v[128:129]
	s_mov_b32 m0, s62
	v_lshl_add_u64 v[216:217], s[36:37], 0, v[130:131]
	global_load_lds_dwordx4 v[214:215], off
	v_lshl_add_u64 v[214:215], s[60:61], 0, v[130:131]
	s_add_i32 m0, s62, 0x2000
	s_nop 0
	global_load_lds_dwordx4 v[214:215], off
	v_lshl_add_u64 v[214:215], s[36:37], 0, v[128:129]
	s_mov_b32 m0, s29
	s_nop 0
	global_load_lds_dwordx4 v[214:215], off
	s_mov_b32 m0, s40
	s_nop 0
	global_load_lds_dwordx4 v[216:217], off
	s_waitcnt vmcnt(8)
	s_waitcnt lgkmcnt(0)
	s_barrier
; #define PG8_STAGE(bufoff, gbase, voff) do { _Pragma("unroll") for (int _i = 0; _i < 2; ++_i) \
;         __builtin_amdgcn_global_load_lds((const unsigned*)((const char*)(gbase) + (voff)[_i]), (LAS unsigned*)(lds + (bufoff) + ldsw + _i * 8192), 16, 0, 0); } while (0)
; #define PG8_LDA(dst, b, h) do { _Pragma("unroll") for (int m = 0; m < 4; ++m) _Pragma("unroll") for (int k = 0; k < 2; ++k) dst[m][k] = *(const LAS bf16x8*)(lds + PG8_SA(b, h) + aoff + m * 2048 + k * 1024); } while (0)
; #define PG8_LDB(dst, b, h) do { _Pragma("unroll") for (int n = 0; n < 2; ++n) _Pragma("unroll") for (int k = 0; k < 2; ++k) dst[n][k] = *(const LAS bf16x8*)(lds + PG8_SB(b, h) + boff + n * 2048 + k * 1024); } while (0)
; #define PG8_MMA(ai, bj, At, Bt) do { __builtin_amdgcn_s_setprio(1); _Pragma("unroll") for (int m = 0; m < 4; ++m) _Pragma("unroll") for (int n = 0; n < 2; ++n) _Pragma("unroll") for (int k = 0; k < 2; ++k) \
;         acc[ai][bj][m][n] = __builtin_amdgcn_mfma_f32_16x16x32_bf16(Bt[n][k], At[m][k], acc[ai][bj][m][n], 0, 0, 0); __builtin_amdgcn_s_setprio(0); } while (0)
; #define PG8_WAIT_V(n) asm volatile("s_waitcnt vmcnt(" #n ")" ::: "memory")
; #define PG8_WAIT_L(n) asm volatile("s_waitcnt lgkmcnt(" #n ")" ::: "memory")
; #define PG8_BAR __builtin_amdgcn_s_barrier()
; #define PG8_SCHED __builtin_amdgcn_sched_barrier(0)
; template <class Epi, bool ALIGN_EPI = true, bool SP2 = true>
; DI void gemm_phase(LAS unsigned char* lds, const Gemm g, const StaticOrder& S, const Epi& E) {
;     ...
;             PG8_WAIT_V(8); PG8_WAIT_L(0); PG8_BAR; PG8_MMA(1, 0, At, B0); PG8_MMA(1, 1, At, B1); PG8_BAR; PG8_SCHED;
;             PG8_LDB(B0, 1, 0); PG8_LDB(B1, 1, 1); PG8_SCHED; PG8_LDA(At, 1, 0); PG8_STAGE(PG8_SA(0, 1), a2 + hstepA, voffA);
;             PG8_WAIT_V(8); PG8_WAIT_L(0); PG8_BAR; PG8_MMA(0, 0, At, B0); PG8_MMA(0, 1, At, B1); PG8_BAR; PG8_SCHED;
	v_mfma_f32_16x16x32_bf16 v[60:63], v[140:143], v[180:183], v[60:63]
	v_mfma_f32_16x16x32_bf16 v[56:59], v[156:159], v[180:183], v[56:59]
	v_mfma_f32_16x16x32_bf16 v[52:55], v[140:143], v[188:191], v[52:55]
	v_mfma_f32_16x16x32_bf16 v[48:51], v[156:159], v[188:191], v[48:51]
	v_mfma_f32_16x16x32_bf16 v[44:47], v[140:143], v[196:199], v[44:47]
	v_mfma_f32_16x16x32_bf16 v[36:39], v[156:159], v[196:199], v[36:39]
	v_mfma_f32_16x16x32_bf16 v[28:31], v[140:143], v[204:207], v[28:31]
	v_mfma_f32_16x16x32_bf16 v[16:19], v[156:159], v[204:207], v[16:19]
	v_mfma_f32_16x16x32_bf16 v[60:63], v[152:155], v[184:187], v[60:63]
	v_mfma_f32_16x16x32_bf16 v[56:59], v[160:163], v[184:187], v[56:59]
	v_mfma_f32_16x16x32_bf16 v[52:55], v[152:155], v[192:195], v[52:55]
	v_mfma_f32_16x16x32_bf16 v[48:51], v[160:163], v[192:195], v[48:51]
	v_mfma_f32_16x16x32_bf16 v[44:47], v[152:155], v[200:203], v[44:47]
	v_mfma_f32_16x16x32_bf16 v[36:39], v[160:163], v[200:203], v[36:39]
	v_mfma_f32_16x16x32_bf16 v[28:31], v[152:155], v[208:211], v[28:31]
	v_mfma_f32_16x16x32_bf16 v[16:19], v[160:163], v[208:211], v[16:19]
	v_mfma_f32_16x16x32_bf16 v[40:43], v[164:167], v[180:183], v[40:43]
	v_mfma_f32_16x16x32_bf16 v[32:35], v[172:175], v[180:183], v[32:35]
	v_mfma_f32_16x16x32_bf16 v[24:27], v[164:167], v[188:191], v[24:27]
	v_mfma_f32_16x16x32_bf16 v[20:23], v[172:175], v[188:191], v[20:23]
	v_mfma_f32_16x16x32_bf16 v[12:15], v[164:167], v[196:199], v[12:15]
	v_mfma_f32_16x16x32_bf16 v[8:11], v[172:175], v[196:199], v[8:11]
	v_mfma_f32_16x16x32_bf16 v[4:7], v[164:167], v[204:207], v[4:7]
	v_mfma_f32_16x16x32_bf16 v[0:3], v[172:175], v[204:207], v[0:3]
	v_mfma_f32_16x16x32_bf16 v[40:43], v[168:171], v[184:187], v[40:43]
	v_mfma_f32_16x16x32_bf16 v[32:35], v[176:179], v[184:187], v[32:35]
	v_mfma_f32_16x16x32_bf16 v[24:27], v[168:171], v[192:195], v[24:27]
	v_mfma_f32_16x16x32_bf16 v[20:23], v[176:179], v[192:195], v[20:23]
	v_mfma_f32_16x16x32_bf16 v[12:15], v[168:171], v[200:203], v[12:15]
	v_mfma_f32_16x16x32_bf16 v[8:11], v[176:179], v[200:203], v[8:11]
	v_mfma_f32_16x16x32_bf16 v[4:7], v[168:171], v[208:211], v[4:7]
	v_mfma_f32_16x16x32_bf16 v[0:3], v[176:179], v[208:211], v[0:3]
	s_barrier
	s_add_i32 s60, 0, 0x18000
	s_add_i32 s61, 0, 0x1c000
	v_add_u32_e32 v160, s60, v147
	v_add_u32_e32 v176, s61, v147
	ds_read_b128 v[140:143], v160
	ds_read_b128 v[152:155], v160 offset:1024
	ds_read_b128 v[156:159], v160 offset:2048
	ds_read_b128 v[160:163], v160 offset:3072
	ds_read_b128 v[164:167], v176
	ds_read_b128 v[168:171], v176 offset:1024
	ds_read_b128 v[172:175], v176 offset:2048
	ds_read_b128 v[176:179], v176 offset:3072
	s_add_u32 s36, s36, 0x100000
	s_addc_u32 s37, s37, 0
	s_mov_b32 m0, s41
	v_lshl_add_u64 v[218:219], s[36:37], 0, v[128:129]
	ds_read_b128 v[180:183], v151 offset:32768
	ds_read_b128 v[184:187], v151 offset:33792
	ds_read_b128 v[188:191], v151 offset:34816
	ds_read_b128 v[192:195], v151 offset:35840
	ds_read_b128 v[196:199], v151 offset:36864
	ds_read_b128 v[200:203], v151 offset:37888
	ds_read_b128 v[204:207], v151 offset:38912
	ds_read_b128 v[208:211], v151 offset:39936
	global_load_lds_dwordx4 v[218:219], off
	v_lshl_add_u64 v[218:219], s[36:37], 0, v[130:131]
	s_mov_b32 m0, s42
	s_nop 0
	global_load_lds_dwordx4 v[218:219], off
	s_waitcnt vmcnt(8)
	s_waitcnt lgkmcnt(0)
	s_barrier
	v_mfma_f32_16x16x32_bf16 v[124:127], v[140:143], v[180:183], v[124:127]
	v_mfma_f32_16x16x32_bf16 v[120:123], v[156:159], v[180:183], v[120:123]
	v_mfma_f32_16x16x32_bf16 v[116:119], v[140:143], v[188:191], v[116:119]
	v_mfma_f32_16x16x32_bf16 v[112:115], v[156:159], v[188:191], v[112:115]
	v_mfma_f32_16x16x32_bf16 v[108:111], v[140:143], v[196:199], v[108:111]
	v_mfma_f32_16x16x32_bf16 v[100:103], v[156:159], v[196:199], v[100:103]
	v_mfma_f32_16x16x32_bf16 v[92:95], v[140:143], v[204:207], v[92:95]
	v_mfma_f32_16x16x32_bf16 v[80:83], v[156:159], v[204:207], v[80:83]
	v_mfma_f32_16x16x32_bf16 v[124:127], v[152:155], v[184:187], v[124:127]
	v_mfma_f32_16x16x32_bf16 v[120:123], v[160:163], v[184:187], v[120:123]
	v_mfma_f32_16x16x32_bf16 v[116:119], v[152:155], v[192:195], v[116:119]
	v_mfma_f32_16x16x32_bf16 v[112:115], v[160:163], v[192:195], v[112:115]
	v_mfma_f32_16x16x32_bf16 v[108:111], v[152:155], v[200:203], v[108:111]
	v_mfma_f32_16x16x32_bf16 v[100:103], v[160:163], v[200:203], v[100:103]
	v_mfma_f32_16x16x32_bf16 v[92:95], v[152:155], v[208:211], v[92:95]
	v_mfma_f32_16x16x32_bf16 v[80:83], v[160:163], v[208:211], v[80:83]
	v_mfma_f32_16x16x32_bf16 v[104:107], v[164:167], v[180:183], v[104:107]
	v_mfma_f32_16x16x32_bf16 v[96:99], v[172:175], v[180:183], v[96:99]
	v_mfma_f32_16x16x32_bf16 v[88:91], v[164:167], v[188:191], v[88:91]
	v_mfma_f32_16x16x32_bf16 v[84:87], v[172:175], v[188:191], v[84:87]
	v_mfma_f32_16x16x32_bf16 v[76:79], v[164:167], v[196:199], v[76:79]
	v_mfma_f32_16x16x32_bf16 v[72:75], v[172:175], v[196:199], v[72:75]
	v_mfma_f32_16x16x32_bf16 v[68:71], v[164:167], v[204:207], v[68:71]
	v_mfma_f32_16x16x32_bf16 v[64:67], v[172:175], v[204:207], v[64:67]
	v_mfma_f32_16x16x32_bf16 v[104:107], v[168:171], v[184:187], v[104:107]
	v_mfma_f32_16x16x32_bf16 v[96:99], v[176:179], v[184:187], v[96:99]
	v_mfma_f32_16x16x32_bf16 v[88:91], v[168:171], v[192:195], v[88:91]
	v_mfma_f32_16x16x32_bf16 v[84:87], v[176:179], v[192:195], v[84:87]
	v_mfma_f32_16x16x32_bf16 v[76:79], v[168:171], v[200:203], v[76:79]
	v_mfma_f32_16x16x32_bf16 v[72:75], v[176:179], v[200:203], v[72:75]
	v_mfma_f32_16x16x32_bf16 v[68:71], v[168:171], v[208:211], v[68:71]
	v_mfma_f32_16x16x32_bf16 v[64:67], v[176:179], v[208:211], v[64:67]
	s_barrier
; #define PG8_STAGE(bufoff, gbase, voff) do { _Pragma("unroll") for (int _i = 0; _i < 2; ++_i) \
;         __builtin_amdgcn_global_load_lds((const unsigned*)((const char*)(gbase) + (voff)[_i]), (LAS unsigned*)(lds + (bufoff) + ldsw + _i * 8192), 16, 0, 0); } while (0)
; #define PG8_LDA(dst, b, h) do { _Pragma("unroll") for (int m = 0; m < 4; ++m) _Pragma("unroll") for (int k = 0; k < 2; ++k) dst[m][k] = *(const LAS bf16x8*)(lds + PG8_SA(b, h) + aoff + m * 2048 + k * 1024); } while (0)
; #define PG8_MMA(ai, bj, At, Bt) do { __builtin_amdgcn_s_setprio(1); _Pragma("unroll") for (int m = 0; m < 4; ++m) _Pragma("unroll") for (int n = 0; n < 2; ++n) _Pragma("unroll") for (int k = 0; k < 2; ++k) \
;         acc[ai][bj][m][n] = __builtin_amdgcn_mfma_f32_16x16x32_bf16(Bt[n][k], At[m][k], acc[ai][bj][m][n], 0, 0, 0); __builtin_amdgcn_s_setprio(0); } while (0)
; #define PG8_WAIT_V(n) asm volatile("s_waitcnt vmcnt(" #n ")" ::: "memory")
; #define PG8_WAIT_L(n) asm volatile("s_waitcnt lgkmcnt(" #n ")" ::: "memory")
; #define PG8_BAR __builtin_amdgcn_s_barrier()
; #define PG8_SCHED __builtin_amdgcn_sched_barrier(0)
; template <class Epi, bool ALIGN_EPI = true, bool SP2 = true>
; DI void gemm_phase(LAS unsigned char* lds, const Gemm g, const StaticOrder& S, const Epi& E) {
;     ...
;             PG8_LDA(At, 1, 1); PG8_STAGE(PG8_SB(1, 0), b3, voffB); PG8_STAGE(PG8_SB(1, 1), b3 + hstepB, voffB); PG8_STAGE(PG8_SA(1, 0), a3, voffA);
;             PG8_WAIT_V(8); PG8_WAIT_L(0); PG8_BAR; PG8_MMA(1, 0, At, B0); PG8_MMA(1, 1, At, B1); PG8_BAR; PG8_SCHED;
;     ...
;         if constexpr (ALIGN_EPI) { if (wr == 0) PG8_BAR; }
	s_add_i32 s36, s60, s39
	v_lshl_add_u64 v[144:145], v[144:145], 0, s[6:7]
	s_mov_b32 m0, s36
	ds_read_b128 v[180:183], v151 offset:49152
	ds_read_b128 v[184:187], v151 offset:50176
	ds_read_b128 v[188:191], v151 offset:51200
	ds_read_b128 v[192:195], v151 offset:52224
	ds_read_b128 v[196:199], v151 offset:53248
	ds_read_b128 v[200:203], v151 offset:54272
	ds_read_b128 v[204:207], v151 offset:55296
	ds_read_b128 v[208:211], v151 offset:56320
	global_load_lds_dwordx4 v[144:145], off
	s_add_i32 m0, s36, 0x2000
	s_add_u32 s34, s34, 0x100080
	v_lshl_add_u64 v[144:145], v[212:213], 0, s[6:7]
	s_addc_u32 s35, s35, 0
	s_add_i32 s36, s61, s39
	global_load_lds_dwordx4 v[144:145], off
	v_lshl_add_u64 v[144:145], s[34:35], 0, v[128:129]
	s_mov_b32 m0, s36
	s_nop 0
	global_load_lds_dwordx4 v[144:145], off
	v_lshl_add_u64 v[144:145], s[34:35], 0, v[130:131]
	s_add_i32 m0, s36, 0x2000
	s_nop 0
	global_load_lds_dwordx4 v[144:145], off
	v_lshl_add_u64 v[144:145], v[214:215], 0, s[6:7]
	s_mov_b32 m0, s44
	s_nop 0
	global_load_lds_dwordx4 v[144:145], off
	v_lshl_add_u64 v[144:145], v[216:217], 0, s[6:7]
	s_mov_b32 m0, s45
	s_nop 0
	global_load_lds_dwordx4 v[144:145], off
	s_waitcnt vmcnt(8)
	s_waitcnt lgkmcnt(0)
	s_barrier
	v_mfma_f32_16x16x32_bf16 v[60:63], v[140:143], v[180:183], v[60:63]
	v_mfma_f32_16x16x32_bf16 v[56:59], v[156:159], v[180:183], v[56:59]
	v_mfma_f32_16x16x32_bf16 v[52:55], v[140:143], v[188:191], v[52:55]
	v_mfma_f32_16x16x32_bf16 v[48:51], v[156:159], v[188:191], v[48:51]
	v_mfma_f32_16x16x32_bf16 v[44:47], v[140:143], v[196:199], v[44:47]
	v_mfma_f32_16x16x32_bf16 v[36:39], v[156:159], v[196:199], v[36:39]
	v_mfma_f32_16x16x32_bf16 v[28:31], v[140:143], v[204:207], v[28:31]
	v_mfma_f32_16x16x32_bf16 v[16:19], v[156:159], v[204:207], v[16:19]
	v_mfma_f32_16x16x32_bf16 v[60:63], v[152:155], v[184:187], v[60:63]
	v_mfma_f32_16x16x32_bf16 v[56:59], v[160:163], v[184:187], v[56:59]
	v_mfma_f32_16x16x32_bf16 v[52:55], v[152:155], v[192:195], v[52:55]
	v_mfma_f32_16x16x32_bf16 v[48:51], v[160:163], v[192:195], v[48:51]
	v_mfma_f32_16x16x32_bf16 v[44:47], v[152:155], v[200:203], v[44:47]
	v_mfma_f32_16x16x32_bf16 v[36:39], v[160:163], v[200:203], v[36:39]
	v_mfma_f32_16x16x32_bf16 v[28:31], v[152:155], v[208:211], v[28:31]
	v_mfma_f32_16x16x32_bf16 v[16:19], v[160:163], v[208:211], v[16:19]
	v_mfma_f32_16x16x32_bf16 v[40:43], v[164:167], v[180:183], v[40:43]
	v_mfma_f32_16x16x32_bf16 v[32:35], v[172:175], v[180:183], v[32:35]
	v_mfma_f32_16x16x32_bf16 v[24:27], v[164:167], v[188:191], v[24:27]
	v_mfma_f32_16x16x32_bf16 v[20:23], v[172:175], v[188:191], v[20:23]
	v_mfma_f32_16x16x32_bf16 v[12:15], v[164:167], v[196:199], v[12:15]
	v_mfma_f32_16x16x32_bf16 v[8:11], v[172:175], v[196:199], v[8:11]
	v_mfma_f32_16x16x32_bf16 v[4:7], v[164:167], v[204:207], v[4:7]
	v_mfma_f32_16x16x32_bf16 v[0:3], v[172:175], v[204:207], v[0:3]
	v_mfma_f32_16x16x32_bf16 v[40:43], v[168:171], v[184:187], v[40:43]
	v_mfma_f32_16x16x32_bf16 v[32:35], v[176:179], v[184:187], v[32:35]
	v_mfma_f32_16x16x32_bf16 v[24:27], v[168:171], v[192:195], v[24:27]
	v_mfma_f32_16x16x32_bf16 v[20:23], v[176:179], v[192:195], v[20:23]
	v_mfma_f32_16x16x32_bf16 v[12:15], v[168:171], v[200:203], v[12:15]
	v_mfma_f32_16x16x32_bf16 v[8:11], v[176:179], v[200:203], v[8:11]
	v_mfma_f32_16x16x32_bf16 v[4:7], v[168:171], v[208:211], v[4:7]
	v_mfma_f32_16x16x32_bf16 v[0:3], v[176:179], v[208:211], v[0:3]
	s_barrier
	s_add_i32 s59, s59, 2
	s_add_u32 s30, s30, 0x100
	s_addc_u32 s31, s31, 0
	s_add_u32 s56, s56, 0x100
	s_addc_u32 s57, s57, 0
	s_cmp_gt_u32 s59, 61
	s_cbranch_scc0 .LBB0_839
	s_and_b64 vcc, exec, s[8:9]
	s_cbranch_vccz .LBB0_842
	s_barrier
